# GEMM mainloops: deleted hipcc per-phase s_setprio 1/0 flips (lever 4 A/B)
# speedup vs baseline: 1.0143x; 1.0143x over previous
.LBB0_422:
	s_add_u32 s54, s52, 0xfffc0080
	s_addc_u32 s55, s53, -1
	s_add_i32 s68, 0, 0x10000
	v_add_u32_e32 v142, s68, v187
	ds_read_b128 v[130:133], v142
	ds_read_b128 v[134:137], v142 offset:1024
	ds_read_b128 v[138:141], v142 offset:2048
	ds_read_b128 v[142:145], v142 offset:3072
	s_cmp_eq_u32 s23, 12
	s_cselect_b32 s57, s5, s55
	s_cselect_b32 s56, s90, s54
	s_cselect_b32 s55, s1, s22
	s_cselect_b32 s54, s91, s94
	v_lshl_add_u64 v[184:185], s[52:53], 0, v[172:173]
	s_add_i32 m0, s41, 0xc000
	ds_read_b128 v[146:149], v189
	ds_read_b128 v[150:153], v189 offset:1024
	ds_read_b128 v[154:157], v189 offset:2048
	ds_read_b128 v[158:161], v189 offset:3072
	ds_read_b128 v[162:165], v189 offset:4096
	ds_read_b128 v[166:169], v189 offset:5120
	ds_read_b128 v[180:183], v189 offset:6144
	ds_read_b128 v[210:213], v189 offset:7168
	global_load_lds_dwordx4 v[184:185], off
	v_lshl_add_u64 v[184:185], s[52:53], 0, v[178:179]
	s_add_i32 m0, s41, 0xe000
	s_nop 0
	global_load_lds_dwordx4 v[184:185], off
	s_waitcnt lgkmcnt(8)
	s_barrier
	s_waitcnt lgkmcnt(0)

	s_waitcnt lgkmcnt(0)
	v_mfma_f32_16x16x32_bf16 v[118:121], v[130:133], v[146:149], v[118:121]
	v_mfma_f32_16x16x32_bf16 v[126:129], v[138:141], v[146:149], v[126:129]
	v_mfma_f32_16x16x32_bf16 v[114:117], v[130:133], v[154:157], v[114:117]
	v_mfma_f32_16x16x32_bf16 v[122:125], v[138:141], v[154:157], v[122:125]
	v_mfma_f32_16x16x32_bf16 v[106:109], v[130:133], v[162:165], v[106:109]
	v_mfma_f32_16x16x32_bf16 v[110:113], v[138:141], v[162:165], v[110:113]
	v_mfma_f32_16x16x32_bf16 v[98:101], v[130:133], v[180:183], v[98:101]
	v_mfma_f32_16x16x32_bf16 v[102:105], v[138:141], v[180:183], v[102:105]
	v_mfma_f32_16x16x32_bf16 v[118:121], v[134:137], v[150:153], v[118:121]
	v_mfma_f32_16x16x32_bf16 v[126:129], v[142:145], v[150:153], v[126:129]
	v_mfma_f32_16x16x32_bf16 v[114:117], v[134:137], v[158:161], v[114:117]
	v_mfma_f32_16x16x32_bf16 v[122:125], v[142:145], v[158:161], v[122:125]
	v_mfma_f32_16x16x32_bf16 v[106:109], v[134:137], v[166:169], v[106:109]
	v_mfma_f32_16x16x32_bf16 v[110:113], v[142:145], v[166:169], v[110:113]
	v_mfma_f32_16x16x32_bf16 v[98:101], v[134:137], v[210:213], v[98:101]
	v_mfma_f32_16x16x32_bf16 v[102:105], v[142:145], v[210:213], v[102:105]

	s_barrier
	s_add_i32 s70, 0, 0x14000
	v_add_u32_e32 v184, s70, v187
	s_add_i32 s68, s68, s40
	ds_read_b128 v[214:217], v184
	ds_read_b128 v[218:221], v184 offset:1024
	ds_read_b128 v[222:225], v184 offset:2048
	ds_read_b128 v[226:229], v184 offset:3072
	v_lshl_add_u64 v[184:185], s[54:55], 0, v[0:1]
	s_mov_b32 m0, s68
	v_lshl_add_u64 v[190:191], s[54:55], 0, v[170:171]
	global_load_lds_dwordx4 v[184:185], off
	s_add_i32 m0, s68, 0x2000
	s_nop 0
	global_load_lds_dwordx4 v[190:191], off
	s_barrier
	s_waitcnt lgkmcnt(0)

	s_waitcnt lgkmcnt(0)
	v_mfma_f32_16x16x32_bf16 v[66:69], v[214:217], v[146:149], v[66:69]
	v_mfma_f32_16x16x32_bf16 v[70:73], v[222:225], v[146:149], v[70:73]
	v_mfma_f32_16x16x32_bf16 v[50:53], v[214:217], v[154:157], v[50:53]
	v_mfma_f32_16x16x32_bf16 v[54:57], v[222:225], v[154:157], v[54:57]
	v_mfma_f32_16x16x32_bf16 v[42:45], v[214:217], v[162:165], v[42:45]
	v_mfma_f32_16x16x32_bf16 v[46:49], v[222:225], v[162:165], v[46:49]
	v_mfma_f32_16x16x32_bf16 v[34:37], v[214:217], v[180:183], v[34:37]
	v_mfma_f32_16x16x32_bf16 v[38:41], v[222:225], v[180:183], v[38:41]
	v_mfma_f32_16x16x32_bf16 v[66:69], v[218:221], v[150:153], v[66:69]
	v_mfma_f32_16x16x32_bf16 v[70:73], v[226:229], v[150:153], v[70:73]
	v_mfma_f32_16x16x32_bf16 v[50:53], v[218:221], v[158:161], v[50:53]
	v_mfma_f32_16x16x32_bf16 v[54:57], v[226:229], v[158:161], v[54:57]
	v_mfma_f32_16x16x32_bf16 v[42:45], v[218:221], v[166:169], v[42:45]
	v_mfma_f32_16x16x32_bf16 v[46:49], v[226:229], v[166:169], v[46:49]
	v_mfma_f32_16x16x32_bf16 v[34:37], v[218:221], v[210:213], v[34:37]
	v_mfma_f32_16x16x32_bf16 v[38:41], v[226:229], v[210:213], v[38:41]

	s_mov_b32 m0, s41
	v_lshl_add_u64 v[202:203], s[56:57], 0, v[0:1]
	s_barrier
	ds_read_b128 v[146:149], v189 offset:16384
	ds_read_b128 v[150:153], v189 offset:17408
	ds_read_b128 v[154:157], v189 offset:18432
	ds_read_b128 v[158:161], v189 offset:19456
	ds_read_b128 v[162:165], v189 offset:20480
	ds_read_b128 v[166:169], v189 offset:21504
	ds_read_b128 v[180:183], v189 offset:22528
	ds_read_b128 v[210:213], v189 offset:23552
	global_load_lds_dwordx4 v[202:203], off
	v_lshl_add_u64 v[204:205], s[56:57], 0, v[170:171]
	s_mov_b32 m0, s42
	s_nop 0
	global_load_lds_dwordx4 v[204:205], off
	s_barrier
	s_waitcnt lgkmcnt(0)

	s_waitcnt lgkmcnt(0)
	v_mfma_f32_16x16x32_bf16 v[90:93], v[130:133], v[146:149], v[90:93]
	v_mfma_f32_16x16x32_bf16 v[94:97], v[138:141], v[146:149], v[94:97]
	v_mfma_f32_16x16x32_bf16 v[82:85], v[130:133], v[154:157], v[82:85]
	v_mfma_f32_16x16x32_bf16 v[86:89], v[138:141], v[154:157], v[86:89]
	v_mfma_f32_16x16x32_bf16 v[74:77], v[130:133], v[162:165], v[74:77]
	v_mfma_f32_16x16x32_bf16 v[78:81], v[138:141], v[162:165], v[78:81]
	v_mfma_f32_16x16x32_bf16 v[58:61], v[130:133], v[180:183], v[58:61]
	v_mfma_f32_16x16x32_bf16 v[62:65], v[138:141], v[180:183], v[62:65]
	v_mfma_f32_16x16x32_bf16 v[90:93], v[134:137], v[150:153], v[90:93]
	v_mfma_f32_16x16x32_bf16 v[94:97], v[142:145], v[150:153], v[94:97]
	v_mfma_f32_16x16x32_bf16 v[82:85], v[134:137], v[158:161], v[82:85]
	v_mfma_f32_16x16x32_bf16 v[86:89], v[142:145], v[158:161], v[86:89]
	v_mfma_f32_16x16x32_bf16 v[74:77], v[134:137], v[166:169], v[74:77]
	v_mfma_f32_16x16x32_bf16 v[78:81], v[142:145], v[166:169], v[78:81]
	v_mfma_f32_16x16x32_bf16 v[58:61], v[134:137], v[210:213], v[58:61]
	v_mfma_f32_16x16x32_bf16 v[62:65], v[142:145], v[210:213], v[62:65]

	s_barrier
	s_add_u32 s68, s54, 0x40000
	s_addc_u32 s69, s55, 0
	s_add_i32 s70, s70, s40
	v_lshl_add_u64 v[130:131], s[68:69], 0, v[0:1]
	s_mov_b32 m0, s70
	s_nop 0
	global_load_lds_dwordx4 v[130:131], off
	v_lshl_add_u64 v[130:131], s[68:69], 0, v[170:171]
	s_add_i32 m0, s70, 0x2000
	s_nop 0
	global_load_lds_dwordx4 v[130:131], off
	s_waitcnt vmcnt(6)
	s_barrier

	v_mfma_f32_16x16x32_bf16 v[26:29], v[214:217], v[146:149], v[26:29]
	v_mfma_f32_16x16x32_bf16 v[30:33], v[222:225], v[146:149], v[30:33]
	v_mfma_f32_16x16x32_bf16 v[18:21], v[214:217], v[154:157], v[18:21]
	v_mfma_f32_16x16x32_bf16 v[22:25], v[222:225], v[154:157], v[22:25]
	v_mfma_f32_16x16x32_bf16 v[10:13], v[214:217], v[162:165], v[10:13]
	v_mfma_f32_16x16x32_bf16 v[14:17], v[222:225], v[162:165], v[14:17]
	v_mfma_f32_16x16x32_bf16 v[2:5], v[214:217], v[180:183], v[2:5]
	v_mfma_f32_16x16x32_bf16 v[6:9], v[222:225], v[180:183], v[6:9]
	v_mfma_f32_16x16x32_bf16 v[26:29], v[218:221], v[150:153], v[26:29]
	v_mfma_f32_16x16x32_bf16 v[30:33], v[226:229], v[150:153], v[30:33]
	v_mfma_f32_16x16x32_bf16 v[18:21], v[218:221], v[158:161], v[18:21]
	v_mfma_f32_16x16x32_bf16 v[22:25], v[226:229], v[158:161], v[22:25]
	v_mfma_f32_16x16x32_bf16 v[10:13], v[218:221], v[166:169], v[10:13]
	v_mfma_f32_16x16x32_bf16 v[14:17], v[226:229], v[166:169], v[14:17]
	v_mfma_f32_16x16x32_bf16 v[2:5], v[218:221], v[210:213], v[2:5]
	v_mfma_f32_16x16x32_bf16 v[6:9], v[226:229], v[210:213], v[6:9]

	s_add_i32 s68, 0, 0x18000
	v_add_u32_e32 v142, s68, v187
	s_barrier
	ds_read_b128 v[130:133], v142
	ds_read_b128 v[134:137], v142 offset:1024
	ds_read_b128 v[138:141], v142 offset:2048
	ds_read_b128 v[142:145], v142 offset:3072
	s_add_u32 s56, s56, 0x40000
	s_addc_u32 s57, s57, 0
	s_mov_b32 m0, s43
	v_lshl_add_u64 v[214:215], s[56:57], 0, v[0:1]
	ds_read_b128 v[146:149], v189 offset:32768
	ds_read_b128 v[150:153], v189 offset:33792
	ds_read_b128 v[154:157], v189 offset:34816
	ds_read_b128 v[158:161], v189 offset:35840
	ds_read_b128 v[162:165], v189 offset:36864
	ds_read_b128 v[166:169], v189 offset:37888
	ds_read_b128 v[180:183], v189 offset:38912
	ds_read_b128 v[210:213], v189 offset:39936
	global_load_lds_dwordx4 v[214:215], off
	v_lshl_add_u64 v[214:215], s[56:57], 0, v[170:171]
	s_mov_b32 m0, s58
	s_nop 0
	global_load_lds_dwordx4 v[214:215], off
	s_waitcnt lgkmcnt(8)
	s_barrier
	s_waitcnt lgkmcnt(0)

	s_waitcnt lgkmcnt(0)
	v_mfma_f32_16x16x32_bf16 v[118:121], v[130:133], v[146:149], v[118:121]
	v_mfma_f32_16x16x32_bf16 v[126:129], v[138:141], v[146:149], v[126:129]
	v_mfma_f32_16x16x32_bf16 v[114:117], v[130:133], v[154:157], v[114:117]
	v_mfma_f32_16x16x32_bf16 v[122:125], v[138:141], v[154:157], v[122:125]
	v_mfma_f32_16x16x32_bf16 v[106:109], v[130:133], v[162:165], v[106:109]
	v_mfma_f32_16x16x32_bf16 v[110:113], v[138:141], v[162:165], v[110:113]
	v_mfma_f32_16x16x32_bf16 v[98:101], v[130:133], v[180:183], v[98:101]
	v_mfma_f32_16x16x32_bf16 v[102:105], v[138:141], v[180:183], v[102:105]
	v_mfma_f32_16x16x32_bf16 v[118:121], v[134:137], v[150:153], v[118:121]
	v_mfma_f32_16x16x32_bf16 v[126:129], v[142:145], v[150:153], v[126:129]
	v_mfma_f32_16x16x32_bf16 v[114:117], v[134:137], v[158:161], v[114:117]
	v_mfma_f32_16x16x32_bf16 v[122:125], v[142:145], v[158:161], v[122:125]
	v_mfma_f32_16x16x32_bf16 v[106:109], v[134:137], v[166:169], v[106:109]
	v_mfma_f32_16x16x32_bf16 v[110:113], v[142:145], v[166:169], v[110:113]
	v_mfma_f32_16x16x32_bf16 v[98:101], v[134:137], v[210:213], v[98:101]
	v_mfma_f32_16x16x32_bf16 v[102:105], v[142:145], v[210:213], v[102:105]

	s_barrier
	s_add_i32 s56, 0, 0x1c000
	s_add_i32 s57, s68, s40
	v_add_u32_e32 v209, s56, v187
	v_lshl_add_u64 v[184:185], v[184:185], 0, s[60:61]
	s_mov_b32 m0, s57
	ds_read_b128 v[214:217], v209
	ds_read_b128 v[218:221], v209 offset:1024
	ds_read_b128 v[222:225], v209 offset:2048
	ds_read_b128 v[226:229], v209 offset:3072
	global_load_lds_dwordx4 v[184:185], off
	v_lshl_add_u64 v[184:185], v[190:191], 0, s[60:61]
	s_add_i32 m0, s57, 0x2000
	s_nop 0
	global_load_lds_dwordx4 v[184:185], off
	s_barrier
	s_waitcnt lgkmcnt(0)

	s_waitcnt lgkmcnt(0)
	v_mfma_f32_16x16x32_bf16 v[66:69], v[214:217], v[146:149], v[66:69]
	v_mfma_f32_16x16x32_bf16 v[70:73], v[222:225], v[146:149], v[70:73]
	v_mfma_f32_16x16x32_bf16 v[50:53], v[214:217], v[154:157], v[50:53]
	v_mfma_f32_16x16x32_bf16 v[54:57], v[222:225], v[154:157], v[54:57]
	v_mfma_f32_16x16x32_bf16 v[42:45], v[214:217], v[162:165], v[42:45]
	v_mfma_f32_16x16x32_bf16 v[46:49], v[222:225], v[162:165], v[46:49]
	v_mfma_f32_16x16x32_bf16 v[34:37], v[214:217], v[180:183], v[34:37]
	v_mfma_f32_16x16x32_bf16 v[38:41], v[222:225], v[180:183], v[38:41]
	v_mfma_f32_16x16x32_bf16 v[66:69], v[218:221], v[150:153], v[66:69]
	v_mfma_f32_16x16x32_bf16 v[70:73], v[226:229], v[150:153], v[70:73]
	v_mfma_f32_16x16x32_bf16 v[50:53], v[218:221], v[158:161], v[50:53]
	v_mfma_f32_16x16x32_bf16 v[54:57], v[226:229], v[158:161], v[54:57]
	v_mfma_f32_16x16x32_bf16 v[42:45], v[218:221], v[166:169], v[42:45]
	v_mfma_f32_16x16x32_bf16 v[46:49], v[226:229], v[166:169], v[46:49]
	v_mfma_f32_16x16x32_bf16 v[34:37], v[218:221], v[210:213], v[34:37]
	v_mfma_f32_16x16x32_bf16 v[38:41], v[226:229], v[210:213], v[38:41]

	s_mov_b32 m0, s63
	v_lshl_add_u64 v[184:185], v[202:203], 0, s[60:61]
	s_barrier
	ds_read_b128 v[146:149], v189 offset:49152
	ds_read_b128 v[150:153], v189 offset:50176
	ds_read_b128 v[154:157], v189 offset:51200
	ds_read_b128 v[158:161], v189 offset:52224
	ds_read_b128 v[162:165], v189 offset:53248
	ds_read_b128 v[166:169], v189 offset:54272
	ds_read_b128 v[180:183], v189 offset:55296
	ds_read_b128 v[210:213], v189 offset:56320
	global_load_lds_dwordx4 v[184:185], off
	v_lshl_add_u64 v[184:185], v[204:205], 0, s[60:61]
	s_mov_b32 m0, s64
	s_nop 0
	global_load_lds_dwordx4 v[184:185], off
	s_barrier
	s_waitcnt lgkmcnt(0)

	s_waitcnt lgkmcnt(0)
	v_mfma_f32_16x16x32_bf16 v[90:93], v[130:133], v[146:149], v[90:93]
	v_mfma_f32_16x16x32_bf16 v[94:97], v[138:141], v[146:149], v[94:97]
	v_mfma_f32_16x16x32_bf16 v[82:85], v[130:133], v[154:157], v[82:85]
	v_mfma_f32_16x16x32_bf16 v[86:89], v[138:141], v[154:157], v[86:89]
	v_mfma_f32_16x16x32_bf16 v[74:77], v[130:133], v[162:165], v[74:77]
	v_mfma_f32_16x16x32_bf16 v[78:81], v[138:141], v[162:165], v[78:81]
	v_mfma_f32_16x16x32_bf16 v[58:61], v[130:133], v[180:183], v[58:61]
	v_mfma_f32_16x16x32_bf16 v[62:65], v[138:141], v[180:183], v[62:65]
	v_mfma_f32_16x16x32_bf16 v[90:93], v[134:137], v[150:153], v[90:93]
	v_mfma_f32_16x16x32_bf16 v[94:97], v[142:145], v[150:153], v[94:97]
	v_mfma_f32_16x16x32_bf16 v[82:85], v[134:137], v[158:161], v[82:85]
	v_mfma_f32_16x16x32_bf16 v[86:89], v[142:145], v[158:161], v[86:89]
	v_mfma_f32_16x16x32_bf16 v[74:77], v[134:137], v[166:169], v[74:77]
	v_mfma_f32_16x16x32_bf16 v[78:81], v[142:145], v[166:169], v[78:81]
	v_mfma_f32_16x16x32_bf16 v[58:61], v[134:137], v[210:213], v[58:61]
	v_mfma_f32_16x16x32_bf16 v[62:65], v[142:145], v[210:213], v[62:65]

	s_barrier
	s_add_u32 s54, s54, 0x40080
	s_addc_u32 s55, s55, 0
	s_add_i32 s56, s56, s40
	v_lshl_add_u64 v[130:131], s[54:55], 0, v[0:1]
	s_mov_b32 m0, s56
	s_nop 0
	global_load_lds_dwordx4 v[130:131], off
	v_lshl_add_u64 v[130:131], s[54:55], 0, v[170:171]
	s_add_i32 m0, s56, 0x2000
	s_nop 0
	global_load_lds_dwordx4 v[130:131], off
	s_waitcnt vmcnt(6)
	s_barrier

	v_mfma_f32_16x16x32_bf16 v[26:29], v[214:217], v[146:149], v[26:29]
	v_mfma_f32_16x16x32_bf16 v[30:33], v[222:225], v[146:149], v[30:33]
	v_mfma_f32_16x16x32_bf16 v[18:21], v[214:217], v[154:157], v[18:21]
	v_mfma_f32_16x16x32_bf16 v[22:25], v[222:225], v[154:157], v[22:25]
	v_mfma_f32_16x16x32_bf16 v[10:13], v[214:217], v[162:165], v[10:13]
	v_mfma_f32_16x16x32_bf16 v[14:17], v[222:225], v[162:165], v[14:17]
	v_mfma_f32_16x16x32_bf16 v[2:5], v[214:217], v[180:183], v[2:5]
	v_mfma_f32_16x16x32_bf16 v[6:9], v[222:225], v[180:183], v[6:9]
	v_mfma_f32_16x16x32_bf16 v[26:29], v[218:221], v[150:153], v[26:29]
	v_mfma_f32_16x16x32_bf16 v[30:33], v[226:229], v[150:153], v[30:33]
	v_mfma_f32_16x16x32_bf16 v[18:21], v[218:221], v[158:161], v[18:21]
	v_mfma_f32_16x16x32_bf16 v[22:25], v[226:229], v[158:161], v[22:25]
	v_mfma_f32_16x16x32_bf16 v[10:13], v[218:221], v[166:169], v[10:13]
	v_mfma_f32_16x16x32_bf16 v[14:17], v[226:229], v[166:169], v[14:17]
	v_mfma_f32_16x16x32_bf16 v[2:5], v[218:221], v[210:213], v[2:5]
	v_mfma_f32_16x16x32_bf16 v[6:9], v[226:229], v[210:213], v[6:9]

	s_add_i32 s23, s23, 2
	s_add_u32 s52, s52, 0x100
	s_addc_u32 s53, s53, 0
	s_add_u32 s94, s94, 0x100
	s_addc_u32 s22, s22, 0
	s_cmp_gt_u32 s23, 13
	s_barrier
	s_cbranch_scc0 .LBB0_422
	s_sub_i32 s1, s67, 32
	s_lshr_b32 s1, s1, 2
	s_add_i32 s1, s1, 1
	s_cmp_gt_i32 s67, 31
	s_cselect_b32 s1, s1, 0
	v_lshl_or_b32 v134, s66, 7, v188
	v_lshl_add_u32 v130, s67, 8, v186
	s_mul_hi_u32 s5, s1, 0x6000
	s_mulk_i32 s1, 0x6000
	v_ashrrev_i32_e32 v135, 31, v134
	s_add_u32 s22, s59, s1
	v_ashrrev_i32_e32 v131, 31, v130
	v_lshlrev_b64 v[180:181], 2, v[134:135]
	s_addc_u32 s23, s62, s5
	v_lshlrev_b64 v[132:133], 12, v[130:131]
	v_lshl_add_u64 v[134:135], s[26:27], 0, v[180:181]
	v_lshl_add_u64 v[190:191], s[22:23], 0, v[180:181]
	v_lshl_add_u64 v[136:137], v[134:135], 0, v[132:133]
	global_load_dwordx4 v[150:153], v[190:191], off
	global_load_dwordx4 v[210:213], v[136:137], off
	s_mov_b64 s[22:23], 0x80000
	v_or_b32_e32 v138, 16, v130
	v_mul_f32_e32 v131, 0xbfb8aa3b, v122
	v_mul_f32_e32 v141, 0xbfb8aa3b, v124
	v_mul_f32_e32 v125, 0xbfb8aa3b, v125
	v_or_b32_e32 v122, 32, v130
	v_or_b32_e32 v124, 48, v130
	v_lshl_add_u64 v[234:235], v[132:133], 0, s[22:23]
	s_mov_b64 s[22:23], 0x90000
	v_ashrrev_i32_e32 v139, 31, v138
	v_mul_f32_e32 v140, 0xbfb8aa3b, v123
	v_ashrrev_i32_e32 v123, 31, v122
	v_exp_f32_e32 v248, v125
	v_ashrrev_i32_e32 v125, 31, v124
	v_lshl_add_u64 v[238:239], v[132:133], 0, s[22:23]
	s_mov_b64 s[22:23], 0xa0000
	v_lshlrev_b64 v[202:203], 12, v[138:139]
	v_mul_f32_e32 v126, 0xbfb8aa3b, v126
	v_mul_f32_e32 v127, 0xbfb8aa3b, v127
	v_mul_f32_e32 v128, 0xbfb8aa3b, v128
	v_mul_f32_e32 v129, 0xbfb8aa3b, v129
	v_lshlrev_b64 v[204:205], 12, v[122:123]
	v_lshlrev_b64 v[236:237], 12, v[124:125]
	v_lshl_add_u64 v[184:185], v[132:133], 0, s[22:23]
	s_mov_b64 s[22:23], 0xb0000
	v_lshl_add_u64 v[138:139], v[134:135], 0, v[202:203]
	v_exp_f32_e32 v209, v126
	v_exp_f32_e32 v242, v127
	v_lshl_add_u64 v[122:123], v[134:135], 0, v[204:205]
	v_exp_f32_e32 v243, v128
	v_exp_f32_e32 v244, v129
	v_lshl_add_u64 v[182:183], v[132:133], 0, s[22:23]
	v_lshl_add_u64 v[124:125], v[134:135], 0, v[236:237]
	v_lshl_add_u64 v[126:127], v[134:135], 0, v[234:235]
	v_lshl_add_u64 v[128:129], v[134:135], 0, v[238:239]
	global_load_dwordx4 v[214:217], v[138:139], off
	global_load_dwordx4 v[218:221], v[122:123], off
	v_exp_f32_e32 v245, v131
	v_exp_f32_e32 v246, v140
	v_exp_f32_e32 v247, v141
	v_lshl_add_u64 v[240:241], s[26:27], 0, v[132:133]
	v_lshl_add_u64 v[130:131], v[134:135], 0, v[184:185]
	v_lshl_add_u64 v[132:133], v[134:135], 0, v[182:183]
	global_load_dwordx4 v[158:161], v[136:137], off offset:256
	global_load_dwordx4 v[154:157], v[138:139], off offset:256
	global_load_dwordx4 v[146:149], v[122:123], off offset:256
	global_load_dwordx4 v[222:225], v[124:125], off
	global_load_dwordx4 v[142:145], v[124:125], off offset:256
	global_load_dwordx4 v[226:229], v[126:127], off
	s_nop 0
	global_load_dwordx4 v[138:141], v[126:127], off offset:256
	global_load_dwordx4 v[230:233], v[128:129], off
	global_load_dwordx4 v[134:137], v[128:129], off offset:256
	global_load_dwordx4 v[166:169], v[130:131], off
	s_nop 0
	global_load_dwordx4 v[126:129], v[130:131], off offset:256
	global_load_dwordx4 v[162:165], v[132:133], off
	global_load_dwordx4 v[122:125], v[132:133], off offset:256
	v_add_f32_e32 v130, 1.0, v209
	v_add_f32_e32 v131, 1.0, v242
	v_add_f32_e32 v132, 1.0, v243
	v_add_f32_e32 v133, 1.0, v244
	v_add_f32_e32 v209, 1.0, v245
	v_rcp_f32_e32 v242, v130
	v_rcp_f32_e32 v243, v131
	v_rcp_f32_e32 v244, v132
	v_rcp_f32_e32 v245, v133
	global_load_dwordx4 v[130:133], v[190:191], off offset:256
	v_mul_f32_e32 v54, 0xbfb8aa3b, v54
	v_mul_f32_e32 v55, 0xbfb8aa3b, v55
	v_mul_f32_e32 v56, 0xbfb8aa3b, v56
	v_mul_f32_e32 v57, 0xbfb8aa3b, v57
	v_exp_f32_e32 v54, v54
	v_exp_f32_e32 v55, v55
	v_exp_f32_e32 v56, v56
	v_exp_f32_e32 v57, v57
	v_mul_f32_e32 v48, 0xbfb8aa3b, v48
	v_add_f32_e32 v54, 1.0, v54
	v_add_f32_e32 v55, 1.0, v55
	v_add_f32_e32 v56, 1.0, v56
	v_add_f32_e32 v57, 1.0, v57
	v_mul_f32_e32 v46, 0xbfb8aa3b, v46
	v_mul_f32_e32 v47, 0xbfb8aa3b, v47
	v_exp_f32_e32 v48, v48
	v_mul_f32_e32 v49, 0xbfb8aa3b, v49
	v_rcp_f32_e32 v54, v54
	v_rcp_f32_e32 v55, v55
	v_rcp_f32_e32 v56, v56
	v_rcp_f32_e32 v57, v57
	v_exp_f32_e32 v46, v46
	v_exp_f32_e32 v47, v47
	v_exp_f32_e32 v49, v49
	v_mul_f32_e32 v88, 0xbfb8aa3b, v88
	v_mul_f32_e32 v89, 0xbfb8aa3b, v89
	v_exp_f32_e32 v88, v88
	v_exp_f32_e32 v89, v89
	v_mul_f32_e32 v80, 0xbfb8aa3b, v80
	v_mul_f32_e32 v81, 0xbfb8aa3b, v81
	v_exp_f32_e32 v80, v80
	v_exp_f32_e32 v81, v81
	v_add_f32_e32 v48, 1.0, v48
	v_mul_f32_e32 v40, 0xbfb8aa3b, v40
	v_pk_mul_f32 v[54:55], v[50:51], v[54:55]
	v_pk_mul_f32 v[50:51], v[52:53], v[56:57]
	v_add_f32_e32 v46, 1.0, v46
	v_add_f32_e32 v47, 1.0, v47
	v_rcp_f32_e32 v52, v48
	v_add_f32_e32 v48, 1.0, v49
	v_mul_f32_e32 v38, 0xbfb8aa3b, v38
	v_mul_f32_e32 v39, 0xbfb8aa3b, v39
	v_exp_f32_e32 v40, v40
	v_mul_f32_e32 v41, 0xbfb8aa3b, v41
	v_rcp_f32_e32 v46, v46
	v_rcp_f32_e32 v47, v47
	v_rcp_f32_e32 v53, v48
	v_exp_f32_e32 v38, v38
	v_exp_f32_e32 v39, v39
	v_exp_f32_e32 v41, v41
	v_add_f32_e32 v88, 1.0, v88
	v_add_f32_e32 v89, 1.0, v89
	v_rcp_f32_e32 v88, v88
	v_rcp_f32_e32 v89, v89
	v_add_f32_e32 v80, 1.0, v80
	v_add_f32_e32 v81, 1.0, v81
	v_rcp_f32_e32 v80, v80
	v_rcp_f32_e32 v81, v81
	v_add_f32_e32 v40, 1.0, v40
	v_mul_f32_e32 v32, 0xbfb8aa3b, v32
	v_pk_mul_f32 v[46:47], v[42:43], v[46:47]
	v_pk_mul_f32 v[42:43], v[44:45], v[52:53]
	v_add_f32_e32 v38, 1.0, v38
	v_add_f32_e32 v39, 1.0, v39
	v_rcp_f32_e32 v44, v40
	v_add_f32_e32 v40, 1.0, v41
	v_mul_f32_e32 v30, 0xbfb8aa3b, v30
	v_mul_f32_e32 v31, 0xbfb8aa3b, v31
	v_exp_f32_e32 v32, v32
	v_mul_f32_e32 v33, 0xbfb8aa3b, v33
	v_mul_f32_e32 v78, 0xbfb8aa3b, v78
	v_rcp_f32_e32 v38, v38
	v_rcp_f32_e32 v39, v39
	v_rcp_f32_e32 v45, v40
	v_exp_f32_e32 v30, v30
	v_exp_f32_e32 v31, v31
	v_exp_f32_e32 v33, v33
	v_pk_mul_f32 v[84:85], v[84:85], v[88:89]
	v_exp_f32_e32 v88, v78
	v_mul_f32_e32 v78, 0xbfb8aa3b, v79
	v_mul_f32_e32 v62, 0xbfb8aa3b, v62
	v_exp_f32_e32 v89, v78
	v_pk_mul_f32 v[76:77], v[76:77], v[80:81]
	v_exp_f32_e32 v80, v62
	v_mul_f32_e32 v62, 0xbfb8aa3b, v63
	v_exp_f32_e32 v81, v62
	v_mul_f32_e32 v64, 0xbfb8aa3b, v64
	v_mul_f32_e32 v65, 0xbfb8aa3b, v65
	v_add_f32_e32 v32, 1.0, v32
	v_mul_f32_e32 v24, 0xbfb8aa3b, v24
	v_mul_f32_e32 v112, 0xbfb8aa3b, v112
	v_mul_f32_e32 v113, 0xbfb8aa3b, v113
	v_mul_f32_e32 v104, 0xbfb8aa3b, v104
	v_mul_f32_e32 v105, 0xbfb8aa3b, v105
	v_mul_f32_e32 v96, 0xbfb8aa3b, v96
	v_mul_f32_e32 v97, 0xbfb8aa3b, v97
	v_exp_f32_e32 v64, v64
	v_exp_f32_e32 v65, v65
	v_pk_mul_f32 v[38:39], v[34:35], v[38:39]
	v_pk_mul_f32 v[34:35], v[36:37], v[44:45]
	v_add_f32_e32 v30, 1.0, v30
	v_add_f32_e32 v31, 1.0, v31
	v_rcp_f32_e32 v36, v32
	v_add_f32_e32 v32, 1.0, v33
	v_mul_f32_e32 v22, 0xbfb8aa3b, v22
	v_mul_f32_e32 v23, 0xbfb8aa3b, v23
	v_exp_f32_e32 v24, v24
	v_mul_f32_e32 v25, 0xbfb8aa3b, v25
	v_exp_f32_e32 v112, v112
	v_exp_f32_e32 v113, v113
	v_exp_f32_e32 v104, v104
	v_exp_f32_e32 v105, v105
	v_exp_f32_e32 v96, v96
	v_exp_f32_e32 v97, v97
	v_rcp_f32_e32 v30, v30
	v_rcp_f32_e32 v31, v31
	v_rcp_f32_e32 v37, v32
	v_exp_f32_e32 v22, v22
	v_exp_f32_e32 v23, v23
	v_exp_f32_e32 v25, v25
	v_add_f32_e32 v88, 1.0, v88
	v_add_f32_e32 v89, 1.0, v89
	v_rcp_f32_e32 v88, v88
	v_rcp_f32_e32 v89, v89
	v_add_f32_e32 v80, 1.0, v80
	v_add_f32_e32 v81, 1.0, v81
	v_pk_mul_f32 v[118:119], v[118:119], v[242:243]
	v_rcp_f32_e32 v80, v80
	v_rcp_f32_e32 v81, v81
	v_add_f32_e32 v64, 1.0, v64
	v_add_f32_e32 v65, 1.0, v65
	v_add_f32_e32 v24, 1.0, v24
	v_mul_f32_e32 v16, 0xbfb8aa3b, v16
	v_add_f32_e32 v250, 1.0, v247
	v_pk_mul_f32 v[120:121], v[120:121], v[244:245]
	s_waitcnt vmcnt(0)
	v_pk_fma_f32 v[210:211], v[118:119], v[150:151], v[210:211]
	v_add_f32_e32 v118, 1.0, v248
	v_add_f32_e32 v112, 1.0, v112
	v_add_f32_e32 v113, 1.0, v113
	v_add_f32_e32 v104, 1.0, v104
	v_add_f32_e32 v105, 1.0, v105
	v_add_f32_e32 v96, 1.0, v96
	v_add_f32_e32 v97, 1.0, v97
	v_rcp_f32_e32 v64, v64
	v_rcp_f32_e32 v65, v65
	v_pk_mul_f32 v[30:31], v[26:27], v[30:31]
	v_pk_mul_f32 v[26:27], v[28:29], v[36:37]
	v_add_f32_e32 v22, 1.0, v22
	v_add_f32_e32 v23, 1.0, v23
	v_rcp_f32_e32 v28, v24
	v_add_f32_e32 v24, 1.0, v25
	v_mul_f32_e32 v14, 0xbfb8aa3b, v14
	v_mul_f32_e32 v15, 0xbfb8aa3b, v15
	v_exp_f32_e32 v16, v16
	v_mul_f32_e32 v17, 0xbfb8aa3b, v17
	v_pk_fma_f32 v[212:213], v[120:121], v[152:153], v[212:213]
	v_rcp_f32_e32 v120, v250
	v_rcp_f32_e32 v121, v118
	v_rcp_f32_e32 v112, v112
	v_rcp_f32_e32 v113, v113
	v_rcp_f32_e32 v104, v104
	v_rcp_f32_e32 v105, v105
	v_rcp_f32_e32 v96, v96
	v_rcp_f32_e32 v97, v97
	v_rcp_f32_e32 v22, v22
	v_rcp_f32_e32 v23, v23
	v_rcp_f32_e32 v29, v24
	v_exp_f32_e32 v14, v14
	v_exp_f32_e32 v15, v15
	v_exp_f32_e32 v17, v17
	v_pk_mul_f32 v[74:75], v[74:75], v[88:89]
	v_lshl_add_u64 v[62:63], s[26:27], 0, v[184:185]
	v_pk_fma_f32 v[76:77], v[76:77], v[152:153], v[168:169]
	v_pk_fma_f32 v[74:75], v[74:75], v[150:151], v[166:167]
	v_lshl_add_u64 v[62:63], v[62:63], 0, v[180:181]
	v_pk_mul_f32 v[58:59], v[58:59], v[80:81]
	v_mul_f32_e32 v110, 0xbfb8aa3b, v110
	v_mul_f32_e32 v102, 0xbfb8aa3b, v102
	v_mul_f32_e32 v94, 0xbfb8aa3b, v94
	v_mul_f32_e32 v86, 0xbfb8aa3b, v86
	global_store_dwordx4 v[62:63], v[74:77], off
	v_pk_mul_f32 v[60:61], v[60:61], v[64:65]
	v_add_f32_e32 v16, 1.0, v16
	v_pk_fma_f32 v[74:75], v[58:59], v[150:151], v[162:163]
	v_mul_f32_e32 v58, 0xbfb8aa3b, v70
	v_mul_f32_e32 v8, 0xbfb8aa3b, v8
	v_pk_mul_f32 v[116:117], v[116:117], v[120:121]
	v_exp_f32_e32 v120, v110
	v_mul_f32_e32 v110, 0xbfb8aa3b, v111
	v_pk_mul_f32 v[108:109], v[108:109], v[112:113]
	v_exp_f32_e32 v112, v102
	v_mul_f32_e32 v102, 0xbfb8aa3b, v103
	v_pk_mul_f32 v[100:101], v[100:101], v[104:105]
	v_exp_f32_e32 v104, v94
	v_mul_f32_e32 v94, 0xbfb8aa3b, v95
	v_pk_mul_f32 v[92:93], v[92:93], v[96:97]
	v_exp_f32_e32 v96, v86
	v_mul_f32_e32 v86, 0xbfb8aa3b, v87
	v_pk_fma_f32 v[76:77], v[60:61], v[152:153], v[164:165]
	v_exp_f32_e32 v60, v58
	v_mul_f32_e32 v58, 0xbfb8aa3b, v71
	v_mul_f32_e32 v64, 0xbfb8aa3b, v72
	v_mul_f32_e32 v65, 0xbfb8aa3b, v73
	v_pk_mul_f32 v[22:23], v[18:19], v[22:23]
	v_pk_mul_f32 v[18:19], v[20:21], v[28:29]
	v_add_f32_e32 v14, 1.0, v14
	v_add_f32_e32 v15, 1.0, v15
	v_rcp_f32_e32 v20, v16
	v_add_f32_e32 v16, 1.0, v17
	v_mul_f32_e32 v6, 0xbfb8aa3b, v6
	v_mul_f32_e32 v7, 0xbfb8aa3b, v7
	v_exp_f32_e32 v8, v8
	v_mul_f32_e32 v9, 0xbfb8aa3b, v9
	v_exp_f32_e32 v121, v110
	v_exp_f32_e32 v113, v102
	v_exp_f32_e32 v105, v94
	v_exp_f32_e32 v97, v86
	v_exp_f32_e32 v61, v58
	v_exp_f32_e32 v64, v64
	v_exp_f32_e32 v65, v65
	v_rcp_f32_e32 v14, v14
	v_rcp_f32_e32 v15, v15
	v_rcp_f32_e32 v21, v16
	v_exp_f32_e32 v6, v6
	v_exp_f32_e32 v7, v7
	v_exp_f32_e32 v9, v9
	v_add_f32_e32 v8, 1.0, v8
	v_add_f32_e32 v249, 1.0, v246
	v_add_f32_e32 v120, 1.0, v120
	v_add_f32_e32 v121, 1.0, v121
	v_add_f32_e32 v112, 1.0, v112
	v_add_f32_e32 v113, 1.0, v113
	v_add_f32_e32 v104, 1.0, v104
	v_add_f32_e32 v105, 1.0, v105
	v_add_f32_e32 v96, 1.0, v96
	v_add_f32_e32 v97, 1.0, v97
	v_add_f32_e32 v60, 1.0, v60
	v_add_f32_e32 v61, 1.0, v61
	v_add_f32_e32 v64, 1.0, v64
	v_add_f32_e32 v65, 1.0, v65
	v_pk_mul_f32 v[14:15], v[10:11], v[14:15]
	v_pk_mul_f32 v[10:11], v[12:13], v[20:21]
	v_add_f32_e32 v6, 1.0, v6
	v_add_f32_e32 v7, 1.0, v7
	v_rcp_f32_e32 v12, v8
	v_add_f32_e32 v8, 1.0, v9
	v_rcp_f32_e32 v246, v209
	v_rcp_f32_e32 v247, v249
	v_rcp_f32_e32 v120, v120
	v_rcp_f32_e32 v121, v121
	v_rcp_f32_e32 v112, v112
	v_rcp_f32_e32 v113, v113
	v_rcp_f32_e32 v104, v104
	v_rcp_f32_e32 v105, v105
	v_rcp_f32_e32 v96, v96
	v_rcp_f32_e32 v97, v97
	v_rcp_f32_e32 v60, v60
	v_rcp_f32_e32 v61, v61
	v_rcp_f32_e32 v64, v64
	v_rcp_f32_e32 v65, v65
	v_rcp_f32_e32 v6, v6
	v_rcp_f32_e32 v7, v7
	v_rcp_f32_e32 v13, v8
	v_pk_mul_f32 v[114:115], v[114:115], v[246:247]
	v_lshl_add_u64 v[110:111], s[26:27], 0, v[202:203]
	v_pk_mul_f32 v[106:107], v[106:107], v[120:121]
	v_lshl_add_u64 v[102:103], s[26:27], 0, v[204:205]
	v_pk_mul_f32 v[98:99], v[98:99], v[112:113]
	v_lshl_add_u64 v[94:95], s[26:27], 0, v[236:237]
	v_pk_mul_f32 v[90:91], v[90:91], v[104:105]
	v_lshl_add_u64 v[86:87], s[26:27], 0, v[234:235]
	v_pk_mul_f32 v[82:83], v[82:83], v[96:97]
	v_lshl_add_u64 v[78:79], s[26:27], 0, v[238:239]
	v_lshl_add_u64 v[58:59], s[26:27], 0, v[182:183]
	v_pk_mul_f32 v[60:61], v[66:67], v[60:61]
	v_pk_mul_f32 v[64:65], v[68:69], v[64:65]
	v_pk_mul_f32 v[2:3], v[2:3], v[6:7]
	v_pk_mul_f32 v[4:5], v[4:5], v[12:13]
	v_lshl_add_u64 v[118:119], v[240:241], 0, v[180:181]
	v_pk_fma_f32 v[116:117], v[116:117], v[152:153], v[216:217]
	v_pk_fma_f32 v[114:115], v[114:115], v[150:151], v[214:215]
	v_lshl_add_u64 v[110:111], v[110:111], 0, v[180:181]
	v_pk_fma_f32 v[108:109], v[108:109], v[152:153], v[220:221]
	v_pk_fma_f32 v[106:107], v[106:107], v[150:151], v[218:219]
	v_lshl_add_u64 v[102:103], v[102:103], 0, v[180:181]
	v_pk_fma_f32 v[100:101], v[100:101], v[152:153], v[224:225]
	v_pk_fma_f32 v[98:99], v[98:99], v[150:151], v[222:223]
	v_lshl_add_u64 v[94:95], v[94:95], 0, v[180:181]
	v_pk_fma_f32 v[92:93], v[92:93], v[152:153], v[228:229]
	v_pk_fma_f32 v[90:91], v[90:91], v[150:151], v[226:227]
	v_lshl_add_u64 v[86:87], v[86:87], 0, v[180:181]
	v_pk_fma_f32 v[84:85], v[84:85], v[152:153], v[232:233]
	v_pk_fma_f32 v[82:83], v[82:83], v[150:151], v[230:231]
	v_lshl_add_u64 v[78:79], v[78:79], 0, v[180:181]
	v_lshl_add_u64 v[58:59], v[58:59], 0, v[180:181]
	v_pk_fma_f32 v[66:67], v[64:65], v[132:133], v[160:161]
	v_pk_fma_f32 v[64:65], v[60:61], v[130:131], v[158:159]
	v_pk_fma_f32 v[50:51], v[50:51], v[132:133], v[156:157]
	v_pk_fma_f32 v[48:49], v[54:55], v[130:131], v[154:155]
	v_pk_fma_f32 v[42:43], v[42:43], v[132:133], v[148:149]
	v_pk_fma_f32 v[40:41], v[46:47], v[130:131], v[146:147]
	v_pk_fma_f32 v[34:35], v[34:35], v[132:133], v[144:145]
	v_pk_fma_f32 v[32:33], v[38:39], v[130:131], v[142:143]
	v_pk_fma_f32 v[26:27], v[26:27], v[132:133], v[140:141]
	v_pk_fma_f32 v[24:25], v[30:31], v[130:131], v[138:139]
	v_pk_fma_f32 v[18:19], v[18:19], v[132:133], v[136:137]
	v_pk_fma_f32 v[16:17], v[22:23], v[130:131], v[134:135]
	v_pk_fma_f32 v[10:11], v[10:11], v[132:133], v[128:129]
	v_pk_fma_f32 v[8:9], v[14:15], v[130:131], v[126:127]
	v_pk_fma_f32 v[4:5], v[4:5], v[132:133], v[124:125]
	v_pk_fma_f32 v[2:3], v[2:3], v[130:131], v[122:123]
	s_and_b64 vcc, exec, s[2:3]
	s_mov_b32 s66, s0
	s_mov_b32 s67, s4
	s_mov_b64 s[54:55], s[18:19]
	s_mov_b64 s[52:53], s[6:7]
	global_store_dwordx4 v[118:119], v[210:213], off
	global_store_dwordx4 v[110:111], v[114:117], off
	global_store_dwordx4 v[102:103], v[106:109], off
	global_store_dwordx4 v[94:95], v[98:101], off
	global_store_dwordx4 v[86:87], v[90:93], off
	global_store_dwordx4 v[78:79], v[82:85], off
	global_store_dwordx4 v[58:59], v[74:77], off
	global_store_dwordx4 v[118:119], v[64:67], off offset:256
	global_store_dwordx4 v[110:111], v[48:51], off offset:256
	global_store_dwordx4 v[102:103], v[40:43], off offset:256
	global_store_dwordx4 v[94:95], v[32:35], off offset:256
	global_store_dwordx4 v[86:87], v[24:27], off offset:256
	global_store_dwordx4 v[78:79], v[16:19], off offset:256
	global_store_dwordx4 v[62:63], v[8:11], off offset:256
	global_store_dwordx4 v[58:59], v[2:5], off offset:256
	s_cbranch_vccz .LBB0_419
	s_waitcnt vmcnt(0)
	v_readlane_b32 s66, v252, 44
	v_readlane_b32 s64, v254, 62
	s_cmpk_gt_u32 s14, 0xff
	v_readlane_b32 s67, v252, 45
	v_readlane_b32 s65, v254, 63
	s_cbranch_scc1 .LBB0_426
	s_barrier

.LBB0_490:
	s_add_u32 s52, s0, 0xfffc0080
	s_addc_u32 s53, s1, -1
	s_add_i32 s68, 0, 0x10000
	v_add_u32_e32 v0, s68, v168
	ds_read_b128 v[122:125], v0
	ds_read_b128 v[126:129], v0 offset:1024
	ds_read_b128 v[134:137], v0 offset:2048
	ds_read_b128 v[138:141], v0 offset:3072
	s_cmp_eq_u32 s23, 12
	s_cselect_b32 s63, s19, s53
	s_cselect_b32 s62, s67, s52
	s_cselect_b32 s53, s55, s22
	s_cselect_b32 s52, vcc_lo, vcc_hi
	v_lshl_add_u64 v[190:191], s[0:1], 0, v[152:153]
	s_add_i32 m0, s21, 0xc000
	ds_read_b128 v[156:159], v169
	ds_read_b128 v[160:163], v169 offset:1024
	ds_read_b128 v[164:167], v169 offset:2048
	ds_read_b128 v[170:173], v169 offset:3072
	ds_read_b128 v[178:181], v169 offset:4096
	ds_read_b128 v[182:185], v169 offset:5120
	ds_read_b128 v[186:189], v169 offset:6144
	ds_read_b128 v[210:213], v169 offset:7168
	global_load_lds_dwordx4 v[190:191], off
	v_lshl_add_u64 v[190:191], s[0:1], 0, v[154:155]
	s_add_i32 m0, s21, 0xe000
	s_nop 0
	global_load_lds_dwordx4 v[190:191], off
	s_waitcnt lgkmcnt(8)
	s_barrier
	s_waitcnt lgkmcnt(0)

	s_waitcnt lgkmcnt(0)
	v_mfma_f32_16x16x32_bf16 v[142:145], v[122:125], v[156:159], v[142:145]
	v_mfma_f32_16x16x32_bf16 v[130:133], v[134:137], v[156:159], v[130:133]
	v_mfma_f32_16x16x32_bf16 v[110:113], v[122:125], v[164:167], v[110:113]
	v_mfma_f32_16x16x32_bf16 v[106:109], v[134:137], v[164:167], v[106:109]
	v_mfma_f32_16x16x32_bf16 v[94:97], v[122:125], v[178:181], v[94:97]
	v_mfma_f32_16x16x32_bf16 v[90:93], v[134:137], v[178:181], v[90:93]
	v_mfma_f32_16x16x32_bf16 v[78:81], v[122:125], v[186:189], v[78:81]
	v_mfma_f32_16x16x32_bf16 v[74:77], v[134:137], v[186:189], v[74:77]
	v_mfma_f32_16x16x32_bf16 v[142:145], v[126:129], v[160:163], v[142:145]
	v_mfma_f32_16x16x32_bf16 v[130:133], v[138:141], v[160:163], v[130:133]
	v_mfma_f32_16x16x32_bf16 v[110:113], v[126:129], v[170:173], v[110:113]
	v_mfma_f32_16x16x32_bf16 v[106:109], v[138:141], v[170:173], v[106:109]
	v_mfma_f32_16x16x32_bf16 v[94:97], v[126:129], v[182:185], v[94:97]
	v_mfma_f32_16x16x32_bf16 v[90:93], v[138:141], v[182:185], v[90:93]
	v_mfma_f32_16x16x32_bf16 v[78:81], v[126:129], v[210:213], v[78:81]
	v_mfma_f32_16x16x32_bf16 v[74:77], v[138:141], v[210:213], v[74:77]

	s_barrier
	s_add_i32 s70, 0, 0x14000
	s_add_i32 s68, s68, s20
	v_add_u32_e32 v0, s70, v168
	v_lshl_add_u64 v[190:191], s[52:53], 0, v[148:149]
	s_mov_b32 m0, s68
	ds_read_b128 v[214:217], v0
	ds_read_b128 v[218:221], v0 offset:1024
	ds_read_b128 v[222:225], v0 offset:2048
	ds_read_b128 v[226:229], v0 offset:3072
	global_load_lds_dwordx4 v[190:191], off
	v_lshl_add_u64 v[202:203], s[52:53], 0, v[146:147]
	s_add_i32 m0, s68, 0x2000
	s_nop 0
	global_load_lds_dwordx4 v[202:203], off
	s_barrier
	s_waitcnt lgkmcnt(0)

	s_waitcnt lgkmcnt(0)
	v_mfma_f32_16x16x32_bf16 v[118:121], v[214:217], v[156:159], v[118:121]
	v_mfma_f32_16x16x32_bf16 v[114:117], v[222:225], v[156:159], v[114:117]
	v_mfma_f32_16x16x32_bf16 v[102:105], v[214:217], v[164:167], v[102:105]
	v_mfma_f32_16x16x32_bf16 v[98:101], v[222:225], v[164:167], v[98:101]
	v_mfma_f32_16x16x32_bf16 v[86:89], v[214:217], v[178:181], v[86:89]
	v_mfma_f32_16x16x32_bf16 v[82:85], v[222:225], v[178:181], v[82:85]
	v_mfma_f32_16x16x32_bf16 v[70:73], v[214:217], v[186:189], v[70:73]
	v_mfma_f32_16x16x32_bf16 v[66:69], v[222:225], v[186:189], v[66:69]
	v_mfma_f32_16x16x32_bf16 v[118:121], v[218:221], v[160:163], v[118:121]
	v_mfma_f32_16x16x32_bf16 v[114:117], v[226:229], v[160:163], v[114:117]
	v_mfma_f32_16x16x32_bf16 v[102:105], v[218:221], v[170:173], v[102:105]
	v_mfma_f32_16x16x32_bf16 v[98:101], v[226:229], v[170:173], v[98:101]
	v_mfma_f32_16x16x32_bf16 v[86:89], v[218:221], v[182:185], v[86:89]
	v_mfma_f32_16x16x32_bf16 v[82:85], v[226:229], v[182:185], v[82:85]
	v_mfma_f32_16x16x32_bf16 v[70:73], v[218:221], v[210:213], v[70:73]
	v_mfma_f32_16x16x32_bf16 v[66:69], v[226:229], v[210:213], v[66:69]

	s_mov_b32 m0, s21
	v_lshl_add_u64 v[204:205], s[62:63], 0, v[148:149]
	s_barrier
	ds_read_b128 v[156:159], v169 offset:16384
	ds_read_b128 v[160:163], v169 offset:17408
	ds_read_b128 v[164:167], v169 offset:18432
	ds_read_b128 v[170:173], v169 offset:19456
	ds_read_b128 v[178:181], v169 offset:20480
	ds_read_b128 v[182:185], v169 offset:21504
	ds_read_b128 v[186:189], v169 offset:22528
	ds_read_b128 v[210:213], v169 offset:23552
	global_load_lds_dwordx4 v[204:205], off
	v_lshl_add_u64 v[230:231], s[62:63], 0, v[146:147]
	s_mov_b32 m0, s40
	s_nop 0
	global_load_lds_dwordx4 v[230:231], off
	s_barrier
	s_waitcnt lgkmcnt(0)

	s_waitcnt lgkmcnt(0)
	v_mfma_f32_16x16x32_bf16 v[62:65], v[122:125], v[156:159], v[62:65]
	v_mfma_f32_16x16x32_bf16 v[58:61], v[134:137], v[156:159], v[58:61]
	v_mfma_f32_16x16x32_bf16 v[46:49], v[122:125], v[164:167], v[46:49]
	v_mfma_f32_16x16x32_bf16 v[42:45], v[134:137], v[164:167], v[42:45]
	v_mfma_f32_16x16x32_bf16 v[30:33], v[122:125], v[178:181], v[30:33]
	v_mfma_f32_16x16x32_bf16 v[26:29], v[134:137], v[178:181], v[26:29]
	v_mfma_f32_16x16x32_bf16 v[14:17], v[122:125], v[186:189], v[14:17]
	v_mfma_f32_16x16x32_bf16 v[10:13], v[134:137], v[186:189], v[10:13]
	v_mfma_f32_16x16x32_bf16 v[62:65], v[126:129], v[160:163], v[62:65]
	v_mfma_f32_16x16x32_bf16 v[58:61], v[138:141], v[160:163], v[58:61]
	v_mfma_f32_16x16x32_bf16 v[46:49], v[126:129], v[170:173], v[46:49]
	v_mfma_f32_16x16x32_bf16 v[42:45], v[138:141], v[170:173], v[42:45]
	v_mfma_f32_16x16x32_bf16 v[30:33], v[126:129], v[182:185], v[30:33]
	v_mfma_f32_16x16x32_bf16 v[26:29], v[138:141], v[182:185], v[26:29]
	v_mfma_f32_16x16x32_bf16 v[14:17], v[126:129], v[210:213], v[14:17]
	v_mfma_f32_16x16x32_bf16 v[10:13], v[138:141], v[210:213], v[10:13]

	s_barrier
	s_add_u32 s68, s52, 0x40000
	s_addc_u32 s69, s53, 0
	s_add_i32 s70, s70, s20
	v_lshl_add_u64 v[122:123], s[68:69], 0, v[148:149]
	s_mov_b32 m0, s70
	s_nop 0
	global_load_lds_dwordx4 v[122:123], off
	v_lshl_add_u64 v[122:123], s[68:69], 0, v[146:147]
	s_add_i32 m0, s70, 0x2000
	s_nop 0
	global_load_lds_dwordx4 v[122:123], off
	s_waitcnt vmcnt(6)
	s_barrier

	v_mfma_f32_16x16x32_bf16 v[54:57], v[214:217], v[156:159], v[54:57]
	v_mfma_f32_16x16x32_bf16 v[50:53], v[222:225], v[156:159], v[50:53]
	v_mfma_f32_16x16x32_bf16 v[38:41], v[214:217], v[164:167], v[38:41]
	v_mfma_f32_16x16x32_bf16 v[34:37], v[222:225], v[164:167], v[34:37]
	v_mfma_f32_16x16x32_bf16 v[22:25], v[214:217], v[178:181], v[22:25]
	v_mfma_f32_16x16x32_bf16 v[18:21], v[222:225], v[178:181], v[18:21]
	v_mfma_f32_16x16x32_bf16 v[6:9], v[214:217], v[186:189], v[6:9]
	v_mfma_f32_16x16x32_bf16 v[2:5], v[222:225], v[186:189], v[2:5]
	v_mfma_f32_16x16x32_bf16 v[54:57], v[218:221], v[160:163], v[54:57]
	v_mfma_f32_16x16x32_bf16 v[50:53], v[226:229], v[160:163], v[50:53]
	v_mfma_f32_16x16x32_bf16 v[38:41], v[218:221], v[170:173], v[38:41]
	v_mfma_f32_16x16x32_bf16 v[34:37], v[226:229], v[170:173], v[34:37]
	v_mfma_f32_16x16x32_bf16 v[22:25], v[218:221], v[182:185], v[22:25]
	v_mfma_f32_16x16x32_bf16 v[18:21], v[226:229], v[182:185], v[18:21]
	v_mfma_f32_16x16x32_bf16 v[6:9], v[218:221], v[210:213], v[6:9]
	v_mfma_f32_16x16x32_bf16 v[2:5], v[226:229], v[210:213], v[2:5]

	s_add_i32 s68, 0, 0x18000
	v_add_u32_e32 v0, s68, v168
	s_barrier
	ds_read_b128 v[122:125], v0
	ds_read_b128 v[126:129], v0 offset:1024
	ds_read_b128 v[134:137], v0 offset:2048
	ds_read_b128 v[138:141], v0 offset:3072
	s_add_u32 s62, s62, 0x40000
	s_addc_u32 s63, s63, 0
	s_mov_b32 m0, s41
	v_lshl_add_u64 v[214:215], s[62:63], 0, v[148:149]
	ds_read_b128 v[156:159], v169 offset:32768
	ds_read_b128 v[160:163], v169 offset:33792
	ds_read_b128 v[164:167], v169 offset:34816
	ds_read_b128 v[170:173], v169 offset:35840
	ds_read_b128 v[178:181], v169 offset:36864
	ds_read_b128 v[182:185], v169 offset:37888
	ds_read_b128 v[186:189], v169 offset:38912
	ds_read_b128 v[210:213], v169 offset:39936
	global_load_lds_dwordx4 v[214:215], off
	v_lshl_add_u64 v[214:215], s[62:63], 0, v[146:147]
	s_mov_b32 m0, s42
	s_nop 0
	global_load_lds_dwordx4 v[214:215], off
	s_waitcnt lgkmcnt(8)
	s_barrier
	s_waitcnt lgkmcnt(0)

	s_waitcnt lgkmcnt(0)
	v_mfma_f32_16x16x32_bf16 v[142:145], v[122:125], v[156:159], v[142:145]
	v_mfma_f32_16x16x32_bf16 v[130:133], v[134:137], v[156:159], v[130:133]
	v_mfma_f32_16x16x32_bf16 v[110:113], v[122:125], v[164:167], v[110:113]
	v_mfma_f32_16x16x32_bf16 v[106:109], v[134:137], v[164:167], v[106:109]
	v_mfma_f32_16x16x32_bf16 v[94:97], v[122:125], v[178:181], v[94:97]
	v_mfma_f32_16x16x32_bf16 v[90:93], v[134:137], v[178:181], v[90:93]
	v_mfma_f32_16x16x32_bf16 v[78:81], v[122:125], v[186:189], v[78:81]
	v_mfma_f32_16x16x32_bf16 v[74:77], v[134:137], v[186:189], v[74:77]
	v_mfma_f32_16x16x32_bf16 v[142:145], v[126:129], v[160:163], v[142:145]
	v_mfma_f32_16x16x32_bf16 v[130:133], v[138:141], v[160:163], v[130:133]
	v_mfma_f32_16x16x32_bf16 v[110:113], v[126:129], v[170:173], v[110:113]
	v_mfma_f32_16x16x32_bf16 v[106:109], v[138:141], v[170:173], v[106:109]
	v_mfma_f32_16x16x32_bf16 v[94:97], v[126:129], v[182:185], v[94:97]
	v_mfma_f32_16x16x32_bf16 v[90:93], v[138:141], v[182:185], v[90:93]
	v_mfma_f32_16x16x32_bf16 v[78:81], v[126:129], v[210:213], v[78:81]
	v_mfma_f32_16x16x32_bf16 v[74:77], v[138:141], v[210:213], v[74:77]

	s_barrier
	s_add_i32 s62, 0, 0x1c000
	s_add_i32 s63, s68, s20
	v_add_u32_e32 v0, s62, v168
	v_lshl_add_u64 v[190:191], v[190:191], 0, s[60:61]
	s_mov_b32 m0, s63
	ds_read_b128 v[214:217], v0
	ds_read_b128 v[218:221], v0 offset:1024
	ds_read_b128 v[222:225], v0 offset:2048
	ds_read_b128 v[226:229], v0 offset:3072
	global_load_lds_dwordx4 v[190:191], off
	v_lshl_add_u64 v[190:191], v[202:203], 0, s[60:61]
	s_add_i32 m0, s63, 0x2000
	s_nop 0
	global_load_lds_dwordx4 v[190:191], off
	s_barrier
	s_waitcnt lgkmcnt(0)

	s_waitcnt lgkmcnt(0)
	v_mfma_f32_16x16x32_bf16 v[118:121], v[214:217], v[156:159], v[118:121]
	v_mfma_f32_16x16x32_bf16 v[114:117], v[222:225], v[156:159], v[114:117]
	v_mfma_f32_16x16x32_bf16 v[102:105], v[214:217], v[164:167], v[102:105]
	v_mfma_f32_16x16x32_bf16 v[98:101], v[222:225], v[164:167], v[98:101]
	v_mfma_f32_16x16x32_bf16 v[86:89], v[214:217], v[178:181], v[86:89]
	v_mfma_f32_16x16x32_bf16 v[82:85], v[222:225], v[178:181], v[82:85]
	v_mfma_f32_16x16x32_bf16 v[70:73], v[214:217], v[186:189], v[70:73]
	v_mfma_f32_16x16x32_bf16 v[66:69], v[222:225], v[186:189], v[66:69]
	v_mfma_f32_16x16x32_bf16 v[118:121], v[218:221], v[160:163], v[118:121]
	v_mfma_f32_16x16x32_bf16 v[114:117], v[226:229], v[160:163], v[114:117]
	v_mfma_f32_16x16x32_bf16 v[102:105], v[218:221], v[170:173], v[102:105]
	v_mfma_f32_16x16x32_bf16 v[98:101], v[226:229], v[170:173], v[98:101]
	v_mfma_f32_16x16x32_bf16 v[86:89], v[218:221], v[182:185], v[86:89]
	v_mfma_f32_16x16x32_bf16 v[82:85], v[226:229], v[182:185], v[82:85]
	v_mfma_f32_16x16x32_bf16 v[70:73], v[218:221], v[210:213], v[70:73]
	v_mfma_f32_16x16x32_bf16 v[66:69], v[226:229], v[210:213], v[66:69]

	s_mov_b32 m0, s95
	v_lshl_add_u64 v[190:191], v[204:205], 0, s[60:61]
	s_barrier
	ds_read_b128 v[156:159], v169 offset:49152
	ds_read_b128 v[160:163], v169 offset:50176
	ds_read_b128 v[164:167], v169 offset:51200
	ds_read_b128 v[170:173], v169 offset:52224
	ds_read_b128 v[178:181], v169 offset:53248
	ds_read_b128 v[182:185], v169 offset:54272
	ds_read_b128 v[186:189], v169 offset:55296
	ds_read_b128 v[210:213], v169 offset:56320
	global_load_lds_dwordx4 v[190:191], off
	v_lshl_add_u64 v[190:191], v[230:231], 0, s[60:61]
	s_mov_b32 m0, s96
	s_nop 0
	global_load_lds_dwordx4 v[190:191], off
	s_barrier
	s_waitcnt lgkmcnt(0)

	s_waitcnt lgkmcnt(0)
	v_mfma_f32_16x16x32_bf16 v[62:65], v[122:125], v[156:159], v[62:65]
	v_mfma_f32_16x16x32_bf16 v[58:61], v[134:137], v[156:159], v[58:61]
	v_mfma_f32_16x16x32_bf16 v[46:49], v[122:125], v[164:167], v[46:49]
	v_mfma_f32_16x16x32_bf16 v[42:45], v[134:137], v[164:167], v[42:45]
	v_mfma_f32_16x16x32_bf16 v[30:33], v[122:125], v[178:181], v[30:33]
	v_mfma_f32_16x16x32_bf16 v[26:29], v[134:137], v[178:181], v[26:29]
	v_mfma_f32_16x16x32_bf16 v[14:17], v[122:125], v[186:189], v[14:17]
	v_mfma_f32_16x16x32_bf16 v[10:13], v[134:137], v[186:189], v[10:13]
	v_mfma_f32_16x16x32_bf16 v[62:65], v[126:129], v[160:163], v[62:65]
	v_mfma_f32_16x16x32_bf16 v[58:61], v[138:141], v[160:163], v[58:61]
	v_mfma_f32_16x16x32_bf16 v[46:49], v[126:129], v[170:173], v[46:49]
	v_mfma_f32_16x16x32_bf16 v[42:45], v[138:141], v[170:173], v[42:45]
	v_mfma_f32_16x16x32_bf16 v[30:33], v[126:129], v[182:185], v[30:33]
	v_mfma_f32_16x16x32_bf16 v[26:29], v[138:141], v[182:185], v[26:29]
	v_mfma_f32_16x16x32_bf16 v[14:17], v[126:129], v[210:213], v[14:17]
	v_mfma_f32_16x16x32_bf16 v[10:13], v[138:141], v[210:213], v[10:13]

	s_barrier
	s_add_u32 s52, s52, 0x40080
	s_addc_u32 s53, s53, 0
	s_add_i32 s62, s62, s20
	v_lshl_add_u64 v[122:123], s[52:53], 0, v[148:149]
	s_mov_b32 m0, s62
	s_nop 0
	global_load_lds_dwordx4 v[122:123], off
	v_lshl_add_u64 v[122:123], s[52:53], 0, v[146:147]
	s_add_i32 m0, s62, 0x2000
	s_nop 0
	global_load_lds_dwordx4 v[122:123], off
	s_waitcnt vmcnt(6)
	s_barrier

	v_mfma_f32_16x16x32_bf16 v[54:57], v[214:217], v[156:159], v[54:57]
	v_mfma_f32_16x16x32_bf16 v[50:53], v[222:225], v[156:159], v[50:53]
	v_mfma_f32_16x16x32_bf16 v[38:41], v[214:217], v[164:167], v[38:41]
	v_mfma_f32_16x16x32_bf16 v[34:37], v[222:225], v[164:167], v[34:37]
	v_mfma_f32_16x16x32_bf16 v[22:25], v[214:217], v[178:181], v[22:25]
	v_mfma_f32_16x16x32_bf16 v[18:21], v[222:225], v[178:181], v[18:21]
	v_mfma_f32_16x16x32_bf16 v[6:9], v[214:217], v[186:189], v[6:9]
	v_mfma_f32_16x16x32_bf16 v[2:5], v[222:225], v[186:189], v[2:5]
	v_mfma_f32_16x16x32_bf16 v[54:57], v[218:221], v[160:163], v[54:57]
	v_mfma_f32_16x16x32_bf16 v[50:53], v[226:229], v[160:163], v[50:53]
	v_mfma_f32_16x16x32_bf16 v[38:41], v[218:221], v[170:173], v[38:41]
	v_mfma_f32_16x16x32_bf16 v[34:37], v[226:229], v[170:173], v[34:37]
	v_mfma_f32_16x16x32_bf16 v[22:25], v[218:221], v[182:185], v[22:25]
	v_mfma_f32_16x16x32_bf16 v[18:21], v[226:229], v[182:185], v[18:21]
	v_mfma_f32_16x16x32_bf16 v[6:9], v[218:221], v[210:213], v[6:9]
	v_mfma_f32_16x16x32_bf16 v[2:5], v[226:229], v[210:213], v[2:5]

	s_add_i32 s23, s23, 2
	s_add_u32 s0, s0, 0x100
	s_addc_u32 s1, s1, 0
	s_add_u32 vcc_hi, vcc_hi, 0x100
	s_addc_u32 s22, s22, 0
	s_cmp_gt_u32 s23, 13
	s_barrier
	s_cbranch_scc0 .LBB0_490
	s_lshl_b32 s0, s14, 2
	s_lshl_b32 s19, s66, 8
	s_and_b32 s0, s0, 12
	s_add_i32 s19, s19, s94
	s_or_b32 s0, s0, s43
	v_or_b32_e32 v156, s19, v151
	s_ashr_i32 s55, s14, 2
	v_lshl_or_b32 v159, s0, 6, v150
	s_movk_i32 s22, 0x2000
	v_lshlrev_b32_e32 v122, 10, v156
	s_mov_b64 s[0:1], -1
	s_cmp_lt_i32 s55, 2
	v_ashrrev_i32_e32 v157, 31, v156
	v_cmp_gt_i32_e32 vcc, s22, v156
	v_lshlrev_b32_e32 v0, 1, v159
	v_and_b32_e32 v160, 0x33c00, v122
	s_cbranch_scc1 .LBB0_557
	s_ashr_i32 s0, s19, 8
	v_lshlrev_b64 v[122:123], 11, v[156:157]
	s_ashr_i32 s1, s0, 31
	v_lshl_add_u64 v[122:123], s[92:93], 0, v[122:123]
	s_lshl_b64 s[0:1], s[0:1], 21
	v_cvt_pk_bf16_f32 v126, v142, v143
	v_cvt_pk_bf16_f32 v127, v144, v145
	v_lshl_add_u64 v[124:125], v[122:123], 0, v[0:1]
	v_lshlrev_b32_e32 v122, 2, v160
	global_store_dwordx2 v[124:125], v[126:127], off
	s_and_saveexec_b64 s[52:53], vcc
	s_cbranch_execz .LBB0_494
	s_add_u32 s22, s6, s0
	s_addc_u32 s23, s7, s1
	v_mov_b32_e32 v123, v1
	v_lshl_add_u64 v[126:127], s[22:23], 0, v[122:123]
	v_lshlrev_b32_e32 v128, 2, v159
	v_mov_b32_e32 v129, v1
	v_lshl_add_u64 v[126:127], v[126:127], 0, v[128:129]
	global_store_dwordx4 v[126:127], v[142:145], off nt

.LBB0_801:
	s_add_u32 s54, s52, 0x100
	s_addc_u32 s55, s53, 0
	s_add_i32 s68, 0, 0x10000
	v_add_u32_e32 v122, s68, v210
	ds_read_b128 v[102:105], v122
	ds_read_b128 v[106:109], v122 offset:1024
	ds_read_b128 v[114:117], v122 offset:2048
	ds_read_b128 v[122:125], v122 offset:3072
	s_cmp_eq_u32 vcc_hi, 12
	s_cselect_b32 s59, s5, s55
	s_cselect_b32 s58, s14, s54
	s_cselect_b32 s57, s1, s23
	s_cselect_b32 s56, vcc_lo, s22
	v_lshl_add_u64 v[188:189], s[52:53], 0, v[180:181]
	s_add_i32 m0, s41, 0xc000
	ds_read_b128 v[146:149], v212
	ds_read_b128 v[150:153], v212 offset:1024
	ds_read_b128 v[154:157], v212 offset:2048
	ds_read_b128 v[158:161], v212 offset:3072
	ds_read_b128 v[162:165], v212 offset:4096
	ds_read_b128 v[166:169], v212 offset:5120
	ds_read_b128 v[170:173], v212 offset:6144
	ds_read_b128 v[184:187], v212 offset:7168
	global_load_lds_dwordx4 v[188:189], off
	v_lshl_add_u64 v[188:189], s[52:53], 0, v[182:183]
	s_add_i32 m0, s41, 0xe000
	s_nop 0
	global_load_lds_dwordx4 v[188:189], off
	s_waitcnt lgkmcnt(8)
	s_barrier
	s_waitcnt lgkmcnt(0)

	s_waitcnt lgkmcnt(0)
	v_mfma_f32_16x16x32_bf16 v[142:145], v[102:105], v[146:149], v[142:145]
	v_mfma_f32_16x16x32_bf16 v[138:141], v[114:117], v[146:149], v[138:141]
	v_mfma_f32_16x16x32_bf16 v[134:137], v[102:105], v[154:157], v[134:137]
	v_mfma_f32_16x16x32_bf16 v[118:121], v[114:117], v[154:157], v[118:121]
	v_mfma_f32_16x16x32_bf16 v[110:113], v[102:105], v[162:165], v[110:113]
	v_mfma_f32_16x16x32_bf16 v[90:93], v[114:117], v[162:165], v[90:93]
	v_mfma_f32_16x16x32_bf16 v[82:85], v[102:105], v[170:173], v[82:85]
	v_mfma_f32_16x16x32_bf16 v[78:81], v[114:117], v[170:173], v[78:81]
	v_mfma_f32_16x16x32_bf16 v[142:145], v[106:109], v[150:153], v[142:145]
	v_mfma_f32_16x16x32_bf16 v[138:141], v[122:125], v[150:153], v[138:141]
	v_mfma_f32_16x16x32_bf16 v[134:137], v[106:109], v[158:161], v[134:137]
	v_mfma_f32_16x16x32_bf16 v[118:121], v[122:125], v[158:161], v[118:121]
	v_mfma_f32_16x16x32_bf16 v[110:113], v[106:109], v[166:169], v[110:113]
	v_mfma_f32_16x16x32_bf16 v[90:93], v[122:125], v[166:169], v[90:93]
	v_mfma_f32_16x16x32_bf16 v[82:85], v[106:109], v[184:187], v[82:85]
	v_mfma_f32_16x16x32_bf16 v[78:81], v[122:125], v[184:187], v[78:81]

	s_barrier
	s_add_i32 s69, 0, 0x14000
	v_add_u32_e32 v202, s69, v210
	s_add_i32 s52, s68, s40
	ds_read_b128 v[188:191], v202
	ds_read_b128 v[214:217], v202 offset:1024
	ds_read_b128 v[218:221], v202 offset:2048
	ds_read_b128 v[222:225], v202 offset:3072
	v_lshl_add_u64 v[202:203], s[56:57], 0, v[0:1]
	s_mov_b32 m0, s52
	v_lshl_add_u64 v[204:205], s[56:57], 0, v[178:179]
	global_load_lds_dwordx4 v[202:203], off
	s_add_i32 m0, s52, 0x2000
	s_nop 0
	global_load_lds_dwordx4 v[204:205], off
	s_barrier
	s_waitcnt lgkmcnt(0)

	s_waitcnt lgkmcnt(0)
	v_mfma_f32_16x16x32_bf16 v[130:133], v[188:191], v[146:149], v[130:133]
	v_mfma_f32_16x16x32_bf16 v[126:129], v[218:221], v[146:149], v[126:129]
	v_mfma_f32_16x16x32_bf16 v[98:101], v[188:191], v[154:157], v[98:101]
	v_mfma_f32_16x16x32_bf16 v[94:97], v[218:221], v[154:157], v[94:97]
	v_mfma_f32_16x16x32_bf16 v[86:89], v[188:191], v[162:165], v[86:89]
	v_mfma_f32_16x16x32_bf16 v[74:77], v[218:221], v[162:165], v[74:77]
	v_mfma_f32_16x16x32_bf16 v[70:73], v[188:191], v[170:173], v[70:73]
	v_mfma_f32_16x16x32_bf16 v[66:69], v[218:221], v[170:173], v[66:69]
	v_mfma_f32_16x16x32_bf16 v[130:133], v[214:217], v[150:153], v[130:133]
	v_mfma_f32_16x16x32_bf16 v[126:129], v[222:225], v[150:153], v[126:129]
	v_mfma_f32_16x16x32_bf16 v[98:101], v[214:217], v[158:161], v[98:101]
	v_mfma_f32_16x16x32_bf16 v[94:97], v[222:225], v[158:161], v[94:97]
	v_mfma_f32_16x16x32_bf16 v[86:89], v[214:217], v[166:169], v[86:89]
	v_mfma_f32_16x16x32_bf16 v[74:77], v[222:225], v[166:169], v[74:77]
	v_mfma_f32_16x16x32_bf16 v[70:73], v[214:217], v[184:187], v[70:73]
	v_mfma_f32_16x16x32_bf16 v[66:69], v[222:225], v[184:187], v[66:69]

	s_mov_b32 m0, s41
	v_lshl_add_u64 v[226:227], s[58:59], 0, v[0:1]
	s_barrier
	ds_read_b128 v[146:149], v212 offset:16384
	ds_read_b128 v[150:153], v212 offset:17408
	ds_read_b128 v[154:157], v212 offset:18432
	ds_read_b128 v[158:161], v212 offset:19456
	ds_read_b128 v[162:165], v212 offset:20480
	ds_read_b128 v[166:169], v212 offset:21504
	ds_read_b128 v[170:173], v212 offset:22528
	ds_read_b128 v[184:187], v212 offset:23552
	global_load_lds_dwordx4 v[226:227], off
	v_lshl_add_u64 v[228:229], s[58:59], 0, v[178:179]
	s_mov_b32 m0, s42
	s_nop 0
	global_load_lds_dwordx4 v[228:229], off
	s_barrier
	s_waitcnt lgkmcnt(0)

	s_waitcnt lgkmcnt(0)
	v_mfma_f32_16x16x32_bf16 v[62:65], v[102:105], v[146:149], v[62:65]
	v_mfma_f32_16x16x32_bf16 v[58:61], v[114:117], v[146:149], v[58:61]
	v_mfma_f32_16x16x32_bf16 v[54:57], v[102:105], v[154:157], v[54:57]
	v_mfma_f32_16x16x32_bf16 v[42:45], v[114:117], v[154:157], v[42:45]
	v_mfma_f32_16x16x32_bf16 v[38:41], v[102:105], v[162:165], v[38:41]
	v_mfma_f32_16x16x32_bf16 v[26:29], v[114:117], v[162:165], v[26:29]
	v_mfma_f32_16x16x32_bf16 v[14:17], v[102:105], v[170:173], v[14:17]
	v_mfma_f32_16x16x32_bf16 v[10:13], v[114:117], v[170:173], v[10:13]
	v_mfma_f32_16x16x32_bf16 v[62:65], v[106:109], v[150:153], v[62:65]
	v_mfma_f32_16x16x32_bf16 v[58:61], v[122:125], v[150:153], v[58:61]
	v_mfma_f32_16x16x32_bf16 v[54:57], v[106:109], v[158:161], v[54:57]
	v_mfma_f32_16x16x32_bf16 v[42:45], v[122:125], v[158:161], v[42:45]
	v_mfma_f32_16x16x32_bf16 v[38:41], v[106:109], v[166:169], v[38:41]
	v_mfma_f32_16x16x32_bf16 v[26:29], v[122:125], v[166:169], v[26:29]
	v_mfma_f32_16x16x32_bf16 v[14:17], v[106:109], v[184:187], v[14:17]
	v_mfma_f32_16x16x32_bf16 v[10:13], v[122:125], v[184:187], v[10:13]

	s_barrier
	s_add_u32 s52, s56, 0x40000
	s_addc_u32 s53, s57, 0
	s_add_i32 s68, s69, s40
	v_lshl_add_u64 v[102:103], s[52:53], 0, v[0:1]
	s_mov_b32 m0, s68
	s_nop 0
	global_load_lds_dwordx4 v[102:103], off
	v_lshl_add_u64 v[102:103], s[52:53], 0, v[178:179]
	s_add_i32 m0, s68, 0x2000
	s_nop 0
	global_load_lds_dwordx4 v[102:103], off
	s_waitcnt vmcnt(6)
	s_barrier

	v_mfma_f32_16x16x32_bf16 v[50:53], v[188:191], v[146:149], v[50:53]
	v_mfma_f32_16x16x32_bf16 v[46:49], v[218:221], v[146:149], v[46:49]
	v_mfma_f32_16x16x32_bf16 v[34:37], v[188:191], v[154:157], v[34:37]
	v_mfma_f32_16x16x32_bf16 v[30:33], v[218:221], v[154:157], v[30:33]
	v_mfma_f32_16x16x32_bf16 v[22:25], v[188:191], v[162:165], v[22:25]
	v_mfma_f32_16x16x32_bf16 v[18:21], v[218:221], v[162:165], v[18:21]
	v_mfma_f32_16x16x32_bf16 v[6:9], v[188:191], v[170:173], v[6:9]
	v_mfma_f32_16x16x32_bf16 v[2:5], v[218:221], v[170:173], v[2:5]
	v_mfma_f32_16x16x32_bf16 v[50:53], v[214:217], v[150:153], v[50:53]
	v_mfma_f32_16x16x32_bf16 v[46:49], v[222:225], v[150:153], v[46:49]
	v_mfma_f32_16x16x32_bf16 v[34:37], v[214:217], v[158:161], v[34:37]
	v_mfma_f32_16x16x32_bf16 v[30:33], v[222:225], v[158:161], v[30:33]
	v_mfma_f32_16x16x32_bf16 v[22:25], v[214:217], v[166:169], v[22:25]
	v_mfma_f32_16x16x32_bf16 v[18:21], v[222:225], v[166:169], v[18:21]
	v_mfma_f32_16x16x32_bf16 v[6:9], v[214:217], v[184:187], v[6:9]
	v_mfma_f32_16x16x32_bf16 v[2:5], v[222:225], v[184:187], v[2:5]

	s_add_i32 s68, 0, 0x18000
	v_add_u32_e32 v122, s68, v210
	s_barrier
	ds_read_b128 v[102:105], v122
	ds_read_b128 v[106:109], v122 offset:1024
	ds_read_b128 v[114:117], v122 offset:2048
	ds_read_b128 v[122:125], v122 offset:3072
	s_add_u32 s52, s58, 0x40000
	s_addc_u32 s53, s59, 0
	s_mov_b32 m0, s43
	v_lshl_add_u64 v[188:189], s[52:53], 0, v[0:1]
	ds_read_b128 v[146:149], v212 offset:32768
	ds_read_b128 v[150:153], v212 offset:33792
	ds_read_b128 v[154:157], v212 offset:34816
	ds_read_b128 v[158:161], v212 offset:35840
	ds_read_b128 v[162:165], v212 offset:36864
	ds_read_b128 v[166:169], v212 offset:37888
	ds_read_b128 v[170:173], v212 offset:38912
	ds_read_b128 v[184:187], v212 offset:39936
	global_load_lds_dwordx4 v[188:189], off
	v_lshl_add_u64 v[188:189], s[52:53], 0, v[178:179]
	s_mov_b32 m0, s62
	s_nop 0
	global_load_lds_dwordx4 v[188:189], off
	s_waitcnt lgkmcnt(8)
	s_barrier
	s_waitcnt lgkmcnt(0)

	s_waitcnt lgkmcnt(0)
	v_mfma_f32_16x16x32_bf16 v[142:145], v[102:105], v[146:149], v[142:145]
	v_mfma_f32_16x16x32_bf16 v[138:141], v[114:117], v[146:149], v[138:141]
	v_mfma_f32_16x16x32_bf16 v[134:137], v[102:105], v[154:157], v[134:137]
	v_mfma_f32_16x16x32_bf16 v[118:121], v[114:117], v[154:157], v[118:121]
	v_mfma_f32_16x16x32_bf16 v[110:113], v[102:105], v[162:165], v[110:113]
	v_mfma_f32_16x16x32_bf16 v[90:93], v[114:117], v[162:165], v[90:93]
	v_mfma_f32_16x16x32_bf16 v[82:85], v[102:105], v[170:173], v[82:85]
	v_mfma_f32_16x16x32_bf16 v[78:81], v[114:117], v[170:173], v[78:81]
	v_mfma_f32_16x16x32_bf16 v[142:145], v[106:109], v[150:153], v[142:145]
	v_mfma_f32_16x16x32_bf16 v[138:141], v[122:125], v[150:153], v[138:141]
	v_mfma_f32_16x16x32_bf16 v[134:137], v[106:109], v[158:161], v[134:137]
	v_mfma_f32_16x16x32_bf16 v[118:121], v[122:125], v[158:161], v[118:121]
	v_mfma_f32_16x16x32_bf16 v[110:113], v[106:109], v[166:169], v[110:113]
	v_mfma_f32_16x16x32_bf16 v[90:93], v[122:125], v[166:169], v[90:93]
	v_mfma_f32_16x16x32_bf16 v[82:85], v[106:109], v[184:187], v[82:85]
	v_mfma_f32_16x16x32_bf16 v[78:81], v[122:125], v[184:187], v[78:81]

	s_barrier
	s_add_i32 s58, 0, 0x1c000
	s_add_i32 s52, s68, s40
	v_add_u32_e32 v213, s58, v210
	v_lshl_add_u64 v[202:203], v[202:203], 0, s[60:61]
	s_mov_b32 m0, s52
	ds_read_b128 v[188:191], v213
	ds_read_b128 v[214:217], v213 offset:1024
	ds_read_b128 v[218:221], v213 offset:2048
	ds_read_b128 v[222:225], v213 offset:3072
	global_load_lds_dwordx4 v[202:203], off
	v_lshl_add_u64 v[202:203], v[204:205], 0, s[60:61]
	s_add_i32 m0, s52, 0x2000
	s_nop 0
	global_load_lds_dwordx4 v[202:203], off
	s_barrier
	s_waitcnt lgkmcnt(0)

	s_waitcnt lgkmcnt(0)
	v_mfma_f32_16x16x32_bf16 v[130:133], v[188:191], v[146:149], v[130:133]
	v_mfma_f32_16x16x32_bf16 v[126:129], v[218:221], v[146:149], v[126:129]
	v_mfma_f32_16x16x32_bf16 v[98:101], v[188:191], v[154:157], v[98:101]
	v_mfma_f32_16x16x32_bf16 v[94:97], v[218:221], v[154:157], v[94:97]
	v_mfma_f32_16x16x32_bf16 v[86:89], v[188:191], v[162:165], v[86:89]
	v_mfma_f32_16x16x32_bf16 v[74:77], v[218:221], v[162:165], v[74:77]
	v_mfma_f32_16x16x32_bf16 v[70:73], v[188:191], v[170:173], v[70:73]
	v_mfma_f32_16x16x32_bf16 v[66:69], v[218:221], v[170:173], v[66:69]
	v_mfma_f32_16x16x32_bf16 v[130:133], v[214:217], v[150:153], v[130:133]
	v_mfma_f32_16x16x32_bf16 v[126:129], v[222:225], v[150:153], v[126:129]
	v_mfma_f32_16x16x32_bf16 v[98:101], v[214:217], v[158:161], v[98:101]
	v_mfma_f32_16x16x32_bf16 v[94:97], v[222:225], v[158:161], v[94:97]
	v_mfma_f32_16x16x32_bf16 v[86:89], v[214:217], v[166:169], v[86:89]
	v_mfma_f32_16x16x32_bf16 v[74:77], v[222:225], v[166:169], v[74:77]
	v_mfma_f32_16x16x32_bf16 v[70:73], v[214:217], v[184:187], v[70:73]
	v_mfma_f32_16x16x32_bf16 v[66:69], v[222:225], v[184:187], v[66:69]

	s_mov_b32 m0, s67
	v_lshl_add_u64 v[202:203], v[226:227], 0, s[60:61]
	s_barrier
	ds_read_b128 v[146:149], v212 offset:49152
	ds_read_b128 v[150:153], v212 offset:50176
	ds_read_b128 v[154:157], v212 offset:51200
	ds_read_b128 v[158:161], v212 offset:52224
	ds_read_b128 v[162:165], v212 offset:53248
	ds_read_b128 v[166:169], v212 offset:54272
	ds_read_b128 v[170:173], v212 offset:55296
	ds_read_b128 v[184:187], v212 offset:56320
	global_load_lds_dwordx4 v[202:203], off
	v_lshl_add_u64 v[202:203], v[228:229], 0, s[60:61]
	s_mov_b32 m0, s90
	s_nop 0
	global_load_lds_dwordx4 v[202:203], off
	s_barrier
	s_waitcnt lgkmcnt(0)

	s_waitcnt lgkmcnt(0)
	v_mfma_f32_16x16x32_bf16 v[62:65], v[102:105], v[146:149], v[62:65]
	v_mfma_f32_16x16x32_bf16 v[58:61], v[114:117], v[146:149], v[58:61]
	v_mfma_f32_16x16x32_bf16 v[54:57], v[102:105], v[154:157], v[54:57]
	v_mfma_f32_16x16x32_bf16 v[42:45], v[114:117], v[154:157], v[42:45]
	v_mfma_f32_16x16x32_bf16 v[38:41], v[102:105], v[162:165], v[38:41]
	v_mfma_f32_16x16x32_bf16 v[26:29], v[114:117], v[162:165], v[26:29]
	v_mfma_f32_16x16x32_bf16 v[14:17], v[102:105], v[170:173], v[14:17]
	v_mfma_f32_16x16x32_bf16 v[10:13], v[114:117], v[170:173], v[10:13]
	v_mfma_f32_16x16x32_bf16 v[62:65], v[106:109], v[150:153], v[62:65]
	v_mfma_f32_16x16x32_bf16 v[58:61], v[122:125], v[150:153], v[58:61]
	v_mfma_f32_16x16x32_bf16 v[54:57], v[106:109], v[158:161], v[54:57]
	v_mfma_f32_16x16x32_bf16 v[42:45], v[122:125], v[158:161], v[42:45]
	v_mfma_f32_16x16x32_bf16 v[38:41], v[106:109], v[166:169], v[38:41]
	v_mfma_f32_16x16x32_bf16 v[26:29], v[122:125], v[166:169], v[26:29]
	v_mfma_f32_16x16x32_bf16 v[14:17], v[106:109], v[184:187], v[14:17]
	v_mfma_f32_16x16x32_bf16 v[10:13], v[122:125], v[184:187], v[10:13]

	s_barrier
	s_add_u32 s52, s56, 0x40080
	s_addc_u32 s53, s57, 0
	s_add_i32 s56, s58, s40
	v_lshl_add_u64 v[102:103], s[52:53], 0, v[0:1]
	s_mov_b32 m0, s56
	s_nop 0
	global_load_lds_dwordx4 v[102:103], off
	v_lshl_add_u64 v[102:103], s[52:53], 0, v[178:179]
	s_add_i32 m0, s56, 0x2000
	s_nop 0
	global_load_lds_dwordx4 v[102:103], off
	s_waitcnt vmcnt(6)
	s_barrier

	v_mfma_f32_16x16x32_bf16 v[50:53], v[188:191], v[146:149], v[50:53]
	v_mfma_f32_16x16x32_bf16 v[46:49], v[218:221], v[146:149], v[46:49]
	v_mfma_f32_16x16x32_bf16 v[34:37], v[188:191], v[154:157], v[34:37]
	v_mfma_f32_16x16x32_bf16 v[30:33], v[218:221], v[154:157], v[30:33]
	v_mfma_f32_16x16x32_bf16 v[22:25], v[188:191], v[162:165], v[22:25]
	v_mfma_f32_16x16x32_bf16 v[18:21], v[218:221], v[162:165], v[18:21]
	v_mfma_f32_16x16x32_bf16 v[6:9], v[188:191], v[170:173], v[6:9]
	v_mfma_f32_16x16x32_bf16 v[2:5], v[218:221], v[170:173], v[2:5]
	v_mfma_f32_16x16x32_bf16 v[50:53], v[214:217], v[150:153], v[50:53]
	v_mfma_f32_16x16x32_bf16 v[46:49], v[222:225], v[150:153], v[46:49]
	v_mfma_f32_16x16x32_bf16 v[34:37], v[214:217], v[158:161], v[34:37]
	v_mfma_f32_16x16x32_bf16 v[30:33], v[222:225], v[158:161], v[30:33]
	v_mfma_f32_16x16x32_bf16 v[22:25], v[214:217], v[166:169], v[22:25]
	v_mfma_f32_16x16x32_bf16 v[18:21], v[222:225], v[166:169], v[18:21]
	v_mfma_f32_16x16x32_bf16 v[6:9], v[214:217], v[184:187], v[6:9]
	v_mfma_f32_16x16x32_bf16 v[2:5], v[222:225], v[184:187], v[2:5]

	s_add_i32 vcc_hi, vcc_hi, 2
	s_add_u32 s22, s22, 0x100
	s_addc_u32 s23, s23, 0
	s_cmp_gt_u32 vcc_hi, 13
	s_mov_b64 s[52:53], s[54:55]
	s_barrier
	s_cbranch_scc0 .LBB0_801
	s_sub_i32 s1, s96, 32
	s_lshr_b32 s1, s1, 2
	s_add_i32 s1, s1, 1
	s_cmp_lt_i32 s96, 32
	v_lshl_or_b32 v102, s97, 8, v211
	s_cselect_b32 s1, 0, s1
	s_mul_hi_u32 s5, s1, 0x6000
	s_mulk_i32 s1, 0x6000
	v_ashrrev_i32_e32 v103, 31, v102
	v_lshl_add_u32 v146, s96, 8, v209
	s_cselect_b32 s23, s65, s94
	s_cselect_b32 s22, s66, s91
	s_add_u32 s52, s63, s1
	v_lshlrev_b64 v[184:185], 2, v[102:103]
	v_ashrrev_i32_e32 v147, 31, v146
	s_addc_u32 s53, s64, s5
	v_lshl_add_u64 v[186:187], s[22:23], 0, v[184:185]
	v_lshlrev_b64 v[188:189], 12, v[146:147]
	v_lshl_add_u64 v[102:103], s[52:53], 0, v[184:185]
	v_lshl_add_u64 v[148:149], v[186:187], 0, v[188:189]
	global_load_dwordx4 v[122:125], v[102:103], off
	global_load_dwordx4 v[114:117], v[102:103], off offset:64
	global_load_dwordx4 v[106:109], v[102:103], off offset:512
	s_nop 0
	global_load_dwordx4 v[102:105], v[102:103], off offset:576
	s_nop 0
	global_load_dwordx4 v[214:217], v[148:149], off
	global_load_dwordx4 v[218:221], v[148:149], off offset:64
	global_load_dwordx4 v[222:225], v[148:149], off offset:512
	global_load_dwordx4 v[226:229], v[148:149], off offset:576
	v_or_b32_e32 v148, 16, v146
	v_ashrrev_i32_e32 v149, 31, v148
	v_lshlrev_b64 v[202:203], 12, v[148:149]
	v_lshl_add_u64 v[148:149], v[186:187], 0, v[202:203]
	global_load_dwordx4 v[230:233], v[148:149], off
	global_load_dwordx4 v[234:237], v[148:149], off offset:64
	global_load_dwordx4 v[238:241], v[148:149], off offset:512
	global_load_dwordx4 v[242:245], v[148:149], off offset:576
	v_or_b32_e32 v148, 32, v146
	v_ashrrev_i32_e32 v149, 31, v148
	v_lshlrev_b64 v[204:205], 12, v[148:149]
	v_lshl_add_u64 v[148:149], v[186:187], 0, v[204:205]
	v_or_b32_e32 v146, 48, v146
	global_load_dwordx4 v[246:249], v[148:149], off
	global_load_dwordx4 v[170:173], v[148:149], off offset:64
	global_load_dwordx4 v[166:169], v[148:149], off offset:512
	global_load_dwordx4 v[162:165], v[148:149], off offset:576
	v_ashrrev_i32_e32 v147, 31, v146
	v_lshlrev_b64 v[190:191], 12, v[146:147]
	v_lshl_add_u64 v[146:147], v[186:187], 0, v[190:191]
	global_load_dwordx4 v[158:161], v[146:147], off
	global_load_dwordx4 v[154:157], v[146:147], off offset:64
	global_load_dwordx4 v[150:153], v[146:147], off offset:512
	s_nop 0
	global_load_dwordx4 v[146:149], v[146:147], off offset:576
	s_mov_b64 s[22:23], 0x80000
	s_and_b64 vcc, exec, s[2:3]
	s_mov_b32 s97, s0
	s_mov_b32 s96, s4
	s_mov_b64 s[54:55], s[18:19]
	s_mov_b64 s[52:53], s[6:7]
	s_waitcnt vmcnt(0)
	v_pk_fma_f32 v[142:143], v[142:143], v[122:123], v[214:215]
	v_lshl_add_u64 v[214:215], s[26:27], 0, v[188:189]
	v_lshl_add_u64 v[214:215], v[214:215], 0, v[184:185]
	v_pk_fma_f32 v[132:133], v[132:133], v[108:109], v[224:225]
	v_pk_fma_f32 v[130:131], v[130:131], v[106:107], v[222:223]
	global_store_dwordx4 v[214:215], v[130:133], off offset:512
	v_pk_fma_f32 v[128:129], v[128:129], v[104:105], v[228:229]
	v_pk_fma_f32 v[100:101], v[100:101], v[108:109], v[240:241]
	v_lshl_add_u64 v[130:131], s[26:27], 0, v[202:203]
	v_lshl_add_u64 v[130:131], v[130:131], 0, v[184:185]
	v_pk_fma_f32 v[98:99], v[98:99], v[106:107], v[238:239]
	global_store_dwordx4 v[130:131], v[98:101], off offset:512
	v_pk_fma_f32 v[126:127], v[126:127], v[102:103], v[226:227]
	v_pk_fma_f32 v[96:97], v[96:97], v[104:105], v[244:245]
	v_lshl_add_u64 v[98:99], s[26:27], 0, v[204:205]
	v_lshl_add_u64 v[98:99], v[98:99], 0, v[184:185]
	v_pk_fma_f32 v[76:77], v[76:77], v[104:105], v[164:165]
	v_pk_fma_f32 v[74:75], v[74:75], v[102:103], v[162:163]
	global_store_dwordx4 v[98:99], v[74:77], off offset:576
	v_pk_fma_f32 v[94:95], v[94:95], v[102:103], v[242:243]
	v_pk_fma_f32 v[144:145], v[144:145], v[124:125], v[216:217]
	v_pk_fma_f32 v[74:75], v[82:83], v[122:123], v[158:159]
	v_lshl_add_u64 v[82:83], s[26:27], 0, v[190:191]
	v_pk_fma_f32 v[76:77], v[84:85], v[124:125], v[160:161]
	v_lshl_add_u64 v[82:83], v[82:83], 0, v[184:185]
	v_pk_fma_f32 v[140:141], v[140:141], v[116:117], v[220:221]
	v_pk_fma_f32 v[138:139], v[138:139], v[114:115], v[218:219]
	global_store_dwordx4 v[214:215], v[126:129], off offset:576
	v_pk_fma_f32 v[120:121], v[120:121], v[116:117], v[236:237]
	v_pk_fma_f32 v[118:119], v[118:119], v[114:115], v[234:235]
	v_pk_fma_f32 v[128:129], v[136:137], v[124:125], v[232:233]
	v_pk_fma_f32 v[126:127], v[134:135], v[122:123], v[230:231]
	global_store_dwordx4 v[130:131], v[94:97], off offset:576
	v_pk_fma_f32 v[92:93], v[92:93], v[116:117], v[172:173]
	v_pk_fma_f32 v[90:91], v[90:91], v[114:115], v[170:171]
	v_pk_fma_f32 v[96:97], v[112:113], v[124:125], v[248:249]
	v_pk_fma_f32 v[94:95], v[110:111], v[122:123], v[246:247]
	v_pk_fma_f32 v[88:89], v[88:89], v[108:109], v[168:169]
	v_pk_fma_f32 v[86:87], v[86:87], v[106:107], v[166:167]
	global_store_dwordx4 v[82:83], v[74:77], off
	v_pk_fma_f32 v[72:73], v[72:73], v[108:109], v[152:153]
	v_pk_fma_f32 v[70:71], v[70:71], v[106:107], v[150:151]
	v_pk_fma_f32 v[76:77], v[80:81], v[116:117], v[156:157]
	v_pk_fma_f32 v[74:75], v[78:79], v[114:115], v[154:155]
	v_pk_fma_f32 v[68:69], v[68:69], v[104:105], v[148:149]
	v_pk_fma_f32 v[66:67], v[66:67], v[102:103], v[146:147]
	v_lshl_add_u64 v[100:101], v[188:189], 0, s[22:23]
	global_store_dwordx4 v[214:215], v[142:145], off
	global_store_dwordx4 v[214:215], v[138:141], off offset:64
	global_store_dwordx4 v[130:131], v[126:129], off
	global_store_dwordx4 v[130:131], v[118:121], off offset:64
	global_store_dwordx4 v[98:99], v[94:97], off
	global_store_dwordx4 v[98:99], v[90:93], off offset:64
	global_store_dwordx4 v[98:99], v[86:89], off offset:512
	global_store_dwordx4 v[82:83], v[74:77], off offset:64
	global_store_dwordx4 v[82:83], v[70:73], off offset:512
	global_store_dwordx4 v[82:83], v[66:69], off offset:576
	s_mov_b64 s[22:23], 0x90000
	v_lshl_add_u64 v[150:151], v[188:189], 0, s[22:23]
	v_lshl_add_u64 v[66:67], v[186:187], 0, v[100:101]
	global_load_dwordx4 v[96:99], v[66:67], off
	global_load_dwordx4 v[110:113], v[66:67], off offset:64
	global_load_dwordx4 v[118:121], v[66:67], off offset:512
	global_load_dwordx4 v[126:129], v[66:67], off offset:576
	s_mov_b64 s[22:23], 0xa0000
	v_lshl_add_u64 v[66:67], v[186:187], 0, v[150:151]
	v_lshl_add_u64 v[152:153], v[188:189], 0, s[22:23]
	global_load_dwordx4 v[130:133], v[66:67], off
	global_load_dwordx4 v[134:137], v[66:67], off offset:64
	global_load_dwordx4 v[138:141], v[66:67], off offset:512
	global_load_dwordx4 v[142:145], v[66:67], off offset:576
	v_lshl_add_u64 v[66:67], v[186:187], 0, v[152:153]
	s_mov_b64 s[22:23], 0xb0000
	global_load_dwordx4 v[146:149], v[66:67], off
	global_load_dwordx4 v[90:93], v[66:67], off offset:64
	global_load_dwordx4 v[86:89], v[66:67], off offset:512
	global_load_dwordx4 v[82:85], v[66:67], off offset:576
	v_lshl_add_u64 v[94:95], v[188:189], 0, s[22:23]
	v_lshl_add_u64 v[66:67], v[186:187], 0, v[94:95]
	global_load_dwordx4 v[78:81], v[66:67], off
	global_load_dwordx4 v[74:77], v[66:67], off offset:64
	global_load_dwordx4 v[70:73], v[66:67], off offset:512
	s_nop 0
	global_load_dwordx4 v[66:69], v[66:67], off offset:576
	s_waitcnt vmcnt(0)
	v_pk_fma_f32 v[62:63], v[62:63], v[122:123], v[96:97]
	v_lshl_add_u64 v[96:97], s[26:27], 0, v[100:101]
	v_lshl_add_u64 v[96:97], v[96:97], 0, v[184:185]
	v_pk_fma_f32 v[52:53], v[52:53], v[108:109], v[120:121]
	v_pk_fma_f32 v[50:51], v[50:51], v[106:107], v[118:119]
	global_store_dwordx4 v[96:97], v[50:53], off offset:512
	v_pk_fma_f32 v[36:37], v[36:37], v[108:109], v[140:141]
	v_pk_fma_f32 v[34:35], v[34:35], v[106:107], v[138:139]
	v_lshl_add_u64 v[50:51], s[26:27], 0, v[150:151]
	v_lshl_add_u64 v[50:51], v[50:51], 0, v[184:185]
	global_store_dwordx4 v[50:51], v[34:37], off offset:512
	v_pk_fma_f32 v[20:21], v[20:21], v[104:105], v[84:85]
	v_pk_fma_f32 v[18:19], v[18:19], v[102:103], v[82:83]
	v_lshl_add_u64 v[34:35], s[26:27], 0, v[152:153]
	v_lshl_add_u64 v[34:35], v[34:35], 0, v[184:185]
	v_pk_fma_f32 v[48:49], v[48:49], v[104:105], v[128:129]
	v_pk_fma_f32 v[46:47], v[46:47], v[102:103], v[126:127]
	v_pk_fma_f32 v[32:33], v[32:33], v[104:105], v[144:145]
	v_pk_fma_f32 v[30:31], v[30:31], v[102:103], v[142:143]
	global_store_dwordx4 v[34:35], v[18:21], off offset:576
	v_pk_fma_f32 v[64:65], v[64:65], v[124:125], v[98:99]
	v_pk_fma_f32 v[60:61], v[60:61], v[116:117], v[112:113]
	v_lshl_add_u64 v[18:19], s[26:27], 0, v[94:95]
	v_pk_fma_f32 v[58:59], v[58:59], v[114:115], v[110:111]
	global_store_dwordx4 v[96:97], v[46:49], off offset:576
	v_pk_fma_f32 v[44:45], v[44:45], v[116:117], v[136:137]
	v_pk_fma_f32 v[42:43], v[42:43], v[114:115], v[134:135]
	v_pk_fma_f32 v[48:49], v[56:57], v[124:125], v[132:133]
	v_pk_fma_f32 v[46:47], v[54:55], v[122:123], v[130:131]
	global_store_dwordx4 v[50:51], v[30:33], off offset:576
	v_pk_fma_f32 v[28:29], v[28:29], v[116:117], v[92:93]
	v_pk_fma_f32 v[26:27], v[26:27], v[114:115], v[90:91]
	v_pk_fma_f32 v[32:33], v[40:41], v[124:125], v[148:149]
	v_pk_fma_f32 v[30:31], v[38:39], v[122:123], v[146:147]
	v_pk_fma_f32 v[24:25], v[24:25], v[108:109], v[88:89]
	v_pk_fma_f32 v[22:23], v[22:23], v[106:107], v[86:87]
	v_pk_fma_f32 v[16:17], v[16:17], v[124:125], v[80:81]
	v_pk_fma_f32 v[14:15], v[14:15], v[122:123], v[78:79]
	v_lshl_add_u64 v[18:19], v[18:19], 0, v[184:185]
	v_pk_fma_f32 v[12:13], v[12:13], v[116:117], v[76:77]
	v_pk_fma_f32 v[10:11], v[10:11], v[114:115], v[74:75]
	v_pk_fma_f32 v[8:9], v[8:9], v[108:109], v[72:73]
	v_pk_fma_f32 v[6:7], v[6:7], v[106:107], v[70:71]
	v_pk_fma_f32 v[4:5], v[4:5], v[104:105], v[68:69]
	v_pk_fma_f32 v[2:3], v[2:3], v[102:103], v[66:67]
	global_store_dwordx4 v[96:97], v[62:65], off
	global_store_dwordx4 v[96:97], v[58:61], off offset:64
	global_store_dwordx4 v[50:51], v[46:49], off
	global_store_dwordx4 v[50:51], v[42:45], off offset:64
	global_store_dwordx4 v[34:35], v[30:33], off
	global_store_dwordx4 v[34:35], v[26:29], off offset:64
	global_store_dwordx4 v[34:35], v[22:25], off offset:512
	global_store_dwordx4 v[18:19], v[14:17], off
	global_store_dwordx4 v[18:19], v[10:13], off offset:64
	global_store_dwordx4 v[18:19], v[6:9], off offset:512
	global_store_dwordx4 v[18:19], v[2:5], off offset:576
	s_cbranch_vccz .LBB0_798
	s_waitcnt vmcnt(0)
	v_readlane_b32 s66, v252, 44
	v_readlane_b32 s96, v254, 60
	v_readlane_b32 s64, v254, 62
	v_readlane_b32 s90, v255, 0
	s_cmpk_gt_u32 s70, 0xff
	v_readlane_b32 s67, v252, 45
	v_readlane_b32 s97, v254, 61
	v_readlane_b32 s65, v254, 63
	v_readlane_b32 s91, v255, 1
	s_cbranch_scc1 .LBB0_805
	s_barrier

.LBB0_960:
	s_add_u32 s54, s52, 0xfffc0080
	s_addc_u32 s55, s53, -1
	s_add_i32 s68, 0, 0x10000
	v_add_u32_e32 v136, s68, v139
	ds_read_b128 v[142:145], v136
	ds_read_b128 v[146:149], v136 offset:1024
	ds_read_b128 v[150:153], v136 offset:2048
	ds_read_b128 v[154:157], v136 offset:3072
	s_cmp_eq_u32 s23, 12
	s_cselect_b32 s57, s5, s55
	s_cselect_b32 s56, s66, s54
	s_cselect_b32 s55, s1, s22
	s_cselect_b32 s54, s67, s90
	v_lshl_add_u64 v[136:137], s[52:53], 0, v[132:133]
	s_add_i32 m0, s41, 0xc000
	ds_read_b128 v[158:161], v141
	ds_read_b128 v[162:165], v141 offset:1024
	ds_read_b128 v[166:169], v141 offset:2048
	ds_read_b128 v[170:173], v141 offset:3072
	ds_read_b128 v[178:181], v141 offset:4096
	ds_read_b128 v[182:185], v141 offset:5120
	ds_read_b128 v[186:189], v141 offset:6144
	ds_read_b128 v[210:213], v141 offset:7168
	global_load_lds_dwordx4 v[136:137], off
	v_lshl_add_u64 v[136:137], s[52:53], 0, v[134:135]
	s_add_i32 m0, s41, 0xe000
	s_nop 0
	global_load_lds_dwordx4 v[136:137], off
	s_waitcnt lgkmcnt(8)
	s_barrier
	s_waitcnt lgkmcnt(0)

	s_waitcnt lgkmcnt(0)
	v_mfma_f32_16x16x32_bf16 v[126:129], v[142:145], v[158:161], v[126:129]
	v_mfma_f32_16x16x32_bf16 v[122:125], v[150:153], v[158:161], v[122:125]
	v_mfma_f32_16x16x32_bf16 v[110:113], v[142:145], v[166:169], v[110:113]
	v_mfma_f32_16x16x32_bf16 v[106:109], v[150:153], v[166:169], v[106:109]
	v_mfma_f32_16x16x32_bf16 v[94:97], v[142:145], v[178:181], v[94:97]
	v_mfma_f32_16x16x32_bf16 v[90:93], v[150:153], v[178:181], v[90:93]
	v_mfma_f32_16x16x32_bf16 v[78:81], v[142:145], v[186:189], v[78:81]
	v_mfma_f32_16x16x32_bf16 v[74:77], v[150:153], v[186:189], v[74:77]
	v_mfma_f32_16x16x32_bf16 v[126:129], v[146:149], v[162:165], v[126:129]
	v_mfma_f32_16x16x32_bf16 v[122:125], v[154:157], v[162:165], v[122:125]
	v_mfma_f32_16x16x32_bf16 v[110:113], v[146:149], v[170:173], v[110:113]
	v_mfma_f32_16x16x32_bf16 v[106:109], v[154:157], v[170:173], v[106:109]
	v_mfma_f32_16x16x32_bf16 v[94:97], v[146:149], v[182:185], v[94:97]
	v_mfma_f32_16x16x32_bf16 v[90:93], v[154:157], v[182:185], v[90:93]
	v_mfma_f32_16x16x32_bf16 v[78:81], v[146:149], v[210:213], v[78:81]
	v_mfma_f32_16x16x32_bf16 v[74:77], v[154:157], v[210:213], v[74:77]

	s_barrier
	s_add_i32 s70, 0, 0x14000
	v_add_u32_e32 v136, s70, v139
	s_add_i32 s68, s68, s40
	ds_read_b128 v[214:217], v136
	ds_read_b128 v[218:221], v136 offset:1024
	ds_read_b128 v[222:225], v136 offset:2048
	ds_read_b128 v[226:229], v136 offset:3072
	v_lshl_add_u64 v[136:137], s[54:55], 0, v[0:1]
	s_mov_b32 m0, s68
	v_lshl_add_u64 v[190:191], s[54:55], 0, v[130:131]
	global_load_lds_dwordx4 v[136:137], off
	s_add_i32 m0, s68, 0x2000
	s_nop 0
	global_load_lds_dwordx4 v[190:191], off
	s_barrier
	s_waitcnt lgkmcnt(0)

	s_waitcnt lgkmcnt(0)
	v_mfma_f32_16x16x32_bf16 v[118:121], v[214:217], v[158:161], v[118:121]
	v_mfma_f32_16x16x32_bf16 v[114:117], v[222:225], v[158:161], v[114:117]
	v_mfma_f32_16x16x32_bf16 v[102:105], v[214:217], v[166:169], v[102:105]
	v_mfma_f32_16x16x32_bf16 v[98:101], v[222:225], v[166:169], v[98:101]
	v_mfma_f32_16x16x32_bf16 v[86:89], v[214:217], v[178:181], v[86:89]
	v_mfma_f32_16x16x32_bf16 v[82:85], v[222:225], v[178:181], v[82:85]
	v_mfma_f32_16x16x32_bf16 v[70:73], v[214:217], v[186:189], v[70:73]
	v_mfma_f32_16x16x32_bf16 v[66:69], v[222:225], v[186:189], v[66:69]
	v_mfma_f32_16x16x32_bf16 v[118:121], v[218:221], v[162:165], v[118:121]
	v_mfma_f32_16x16x32_bf16 v[114:117], v[226:229], v[162:165], v[114:117]
	v_mfma_f32_16x16x32_bf16 v[102:105], v[218:221], v[170:173], v[102:105]
	v_mfma_f32_16x16x32_bf16 v[98:101], v[226:229], v[170:173], v[98:101]
	v_mfma_f32_16x16x32_bf16 v[86:89], v[218:221], v[182:185], v[86:89]
	v_mfma_f32_16x16x32_bf16 v[82:85], v[226:229], v[182:185], v[82:85]
	v_mfma_f32_16x16x32_bf16 v[70:73], v[218:221], v[210:213], v[70:73]
	v_mfma_f32_16x16x32_bf16 v[66:69], v[226:229], v[210:213], v[66:69]

	s_mov_b32 m0, s41
	v_lshl_add_u64 v[202:203], s[56:57], 0, v[0:1]
	s_barrier
	ds_read_b128 v[158:161], v141 offset:16384
	ds_read_b128 v[162:165], v141 offset:17408
	ds_read_b128 v[166:169], v141 offset:18432
	ds_read_b128 v[170:173], v141 offset:19456
	ds_read_b128 v[178:181], v141 offset:20480
	ds_read_b128 v[182:185], v141 offset:21504
	ds_read_b128 v[186:189], v141 offset:22528
	ds_read_b128 v[210:213], v141 offset:23552
	global_load_lds_dwordx4 v[202:203], off
	v_lshl_add_u64 v[204:205], s[56:57], 0, v[130:131]
	s_mov_b32 m0, s42
	s_nop 0
	global_load_lds_dwordx4 v[204:205], off
	s_barrier
	s_waitcnt lgkmcnt(0)

	s_waitcnt lgkmcnt(0)
	v_mfma_f32_16x16x32_bf16 v[62:65], v[142:145], v[158:161], v[62:65]
	v_mfma_f32_16x16x32_bf16 v[58:61], v[150:153], v[158:161], v[58:61]
	v_mfma_f32_16x16x32_bf16 v[46:49], v[142:145], v[166:169], v[46:49]
	v_mfma_f32_16x16x32_bf16 v[42:45], v[150:153], v[166:169], v[42:45]
	v_mfma_f32_16x16x32_bf16 v[30:33], v[142:145], v[178:181], v[30:33]
	v_mfma_f32_16x16x32_bf16 v[26:29], v[150:153], v[178:181], v[26:29]
	v_mfma_f32_16x16x32_bf16 v[14:17], v[142:145], v[186:189], v[14:17]
	v_mfma_f32_16x16x32_bf16 v[10:13], v[150:153], v[186:189], v[10:13]
	v_mfma_f32_16x16x32_bf16 v[62:65], v[146:149], v[162:165], v[62:65]
	v_mfma_f32_16x16x32_bf16 v[58:61], v[154:157], v[162:165], v[58:61]
	v_mfma_f32_16x16x32_bf16 v[46:49], v[146:149], v[170:173], v[46:49]
	v_mfma_f32_16x16x32_bf16 v[42:45], v[154:157], v[170:173], v[42:45]
	v_mfma_f32_16x16x32_bf16 v[30:33], v[146:149], v[182:185], v[30:33]
	v_mfma_f32_16x16x32_bf16 v[26:29], v[154:157], v[182:185], v[26:29]
	v_mfma_f32_16x16x32_bf16 v[14:17], v[146:149], v[210:213], v[14:17]
	v_mfma_f32_16x16x32_bf16 v[10:13], v[154:157], v[210:213], v[10:13]

	s_barrier
	s_add_u32 s68, s54, 0x40000
	s_addc_u32 s69, s55, 0
	s_add_i32 s70, s70, s40
	v_lshl_add_u64 v[142:143], s[68:69], 0, v[0:1]
	s_mov_b32 m0, s70
	s_nop 0
	global_load_lds_dwordx4 v[142:143], off
	v_lshl_add_u64 v[142:143], s[68:69], 0, v[130:131]
	s_add_i32 m0, s70, 0x2000
	s_nop 0
	global_load_lds_dwordx4 v[142:143], off
	s_waitcnt vmcnt(6)
	s_barrier

	v_mfma_f32_16x16x32_bf16 v[54:57], v[214:217], v[158:161], v[54:57]
	v_mfma_f32_16x16x32_bf16 v[50:53], v[222:225], v[158:161], v[50:53]
	v_mfma_f32_16x16x32_bf16 v[38:41], v[214:217], v[166:169], v[38:41]
	v_mfma_f32_16x16x32_bf16 v[34:37], v[222:225], v[166:169], v[34:37]
	v_mfma_f32_16x16x32_bf16 v[22:25], v[214:217], v[178:181], v[22:25]
	v_mfma_f32_16x16x32_bf16 v[18:21], v[222:225], v[178:181], v[18:21]
	v_mfma_f32_16x16x32_bf16 v[6:9], v[214:217], v[186:189], v[6:9]
	v_mfma_f32_16x16x32_bf16 v[2:5], v[222:225], v[186:189], v[2:5]
	v_mfma_f32_16x16x32_bf16 v[54:57], v[218:221], v[162:165], v[54:57]
	v_mfma_f32_16x16x32_bf16 v[50:53], v[226:229], v[162:165], v[50:53]
	v_mfma_f32_16x16x32_bf16 v[38:41], v[218:221], v[170:173], v[38:41]
	v_mfma_f32_16x16x32_bf16 v[34:37], v[226:229], v[170:173], v[34:37]
	v_mfma_f32_16x16x32_bf16 v[22:25], v[218:221], v[182:185], v[22:25]
	v_mfma_f32_16x16x32_bf16 v[18:21], v[226:229], v[182:185], v[18:21]
	v_mfma_f32_16x16x32_bf16 v[6:9], v[218:221], v[210:213], v[6:9]
	v_mfma_f32_16x16x32_bf16 v[2:5], v[226:229], v[210:213], v[2:5]

	s_add_i32 s68, 0, 0x18000
	v_add_u32_e32 v154, s68, v139
	s_barrier
	ds_read_b128 v[142:145], v154
	ds_read_b128 v[146:149], v154 offset:1024
	ds_read_b128 v[150:153], v154 offset:2048
	ds_read_b128 v[154:157], v154 offset:3072
	s_add_u32 s56, s56, 0x40000
	s_addc_u32 s57, s57, 0
	s_mov_b32 m0, s43
	v_lshl_add_u64 v[214:215], s[56:57], 0, v[0:1]
	ds_read_b128 v[158:161], v141 offset:32768
	ds_read_b128 v[162:165], v141 offset:33792
	ds_read_b128 v[166:169], v141 offset:34816
	ds_read_b128 v[170:173], v141 offset:35840
	ds_read_b128 v[178:181], v141 offset:36864
	ds_read_b128 v[182:185], v141 offset:37888
	ds_read_b128 v[186:189], v141 offset:38912
	ds_read_b128 v[210:213], v141 offset:39936
	global_load_lds_dwordx4 v[214:215], off
	v_lshl_add_u64 v[214:215], s[56:57], 0, v[130:131]
	s_mov_b32 m0, s58
	s_nop 0
	global_load_lds_dwordx4 v[214:215], off
	s_waitcnt lgkmcnt(8)
	s_barrier
	s_waitcnt lgkmcnt(0)

	s_waitcnt lgkmcnt(0)
	v_mfma_f32_16x16x32_bf16 v[126:129], v[142:145], v[158:161], v[126:129]
	v_mfma_f32_16x16x32_bf16 v[122:125], v[150:153], v[158:161], v[122:125]
	v_mfma_f32_16x16x32_bf16 v[110:113], v[142:145], v[166:169], v[110:113]
	v_mfma_f32_16x16x32_bf16 v[106:109], v[150:153], v[166:169], v[106:109]
	v_mfma_f32_16x16x32_bf16 v[94:97], v[142:145], v[178:181], v[94:97]
	v_mfma_f32_16x16x32_bf16 v[90:93], v[150:153], v[178:181], v[90:93]
	v_mfma_f32_16x16x32_bf16 v[78:81], v[142:145], v[186:189], v[78:81]
	v_mfma_f32_16x16x32_bf16 v[74:77], v[150:153], v[186:189], v[74:77]
	v_mfma_f32_16x16x32_bf16 v[126:129], v[146:149], v[162:165], v[126:129]
	v_mfma_f32_16x16x32_bf16 v[122:125], v[154:157], v[162:165], v[122:125]
	v_mfma_f32_16x16x32_bf16 v[110:113], v[146:149], v[170:173], v[110:113]
	v_mfma_f32_16x16x32_bf16 v[106:109], v[154:157], v[170:173], v[106:109]
	v_mfma_f32_16x16x32_bf16 v[94:97], v[146:149], v[182:185], v[94:97]
	v_mfma_f32_16x16x32_bf16 v[90:93], v[154:157], v[182:185], v[90:93]
	v_mfma_f32_16x16x32_bf16 v[78:81], v[146:149], v[210:213], v[78:81]
	v_mfma_f32_16x16x32_bf16 v[74:77], v[154:157], v[210:213], v[74:77]

	s_barrier
	s_add_i32 s56, 0, 0x1c000
	s_add_i32 s57, s68, s40
	v_add_u32_e32 v209, s56, v139
	v_lshl_add_u64 v[136:137], v[136:137], 0, s[60:61]
	s_mov_b32 m0, s57
	ds_read_b128 v[214:217], v209
	ds_read_b128 v[218:221], v209 offset:1024
	ds_read_b128 v[222:225], v209 offset:2048
	ds_read_b128 v[226:229], v209 offset:3072
	global_load_lds_dwordx4 v[136:137], off
	v_lshl_add_u64 v[136:137], v[190:191], 0, s[60:61]
	s_add_i32 m0, s57, 0x2000
	s_nop 0
	global_load_lds_dwordx4 v[136:137], off
	s_barrier
	s_waitcnt lgkmcnt(0)

	s_waitcnt lgkmcnt(0)
	v_mfma_f32_16x16x32_bf16 v[118:121], v[214:217], v[158:161], v[118:121]
	v_mfma_f32_16x16x32_bf16 v[114:117], v[222:225], v[158:161], v[114:117]
	v_mfma_f32_16x16x32_bf16 v[102:105], v[214:217], v[166:169], v[102:105]
	v_mfma_f32_16x16x32_bf16 v[98:101], v[222:225], v[166:169], v[98:101]
	v_mfma_f32_16x16x32_bf16 v[86:89], v[214:217], v[178:181], v[86:89]
	v_mfma_f32_16x16x32_bf16 v[82:85], v[222:225], v[178:181], v[82:85]
	v_mfma_f32_16x16x32_bf16 v[70:73], v[214:217], v[186:189], v[70:73]
	v_mfma_f32_16x16x32_bf16 v[66:69], v[222:225], v[186:189], v[66:69]
	v_mfma_f32_16x16x32_bf16 v[118:121], v[218:221], v[162:165], v[118:121]
	v_mfma_f32_16x16x32_bf16 v[114:117], v[226:229], v[162:165], v[114:117]
	v_mfma_f32_16x16x32_bf16 v[102:105], v[218:221], v[170:173], v[102:105]
	v_mfma_f32_16x16x32_bf16 v[98:101], v[226:229], v[170:173], v[98:101]
	v_mfma_f32_16x16x32_bf16 v[86:89], v[218:221], v[182:185], v[86:89]
	v_mfma_f32_16x16x32_bf16 v[82:85], v[226:229], v[182:185], v[82:85]
	v_mfma_f32_16x16x32_bf16 v[70:73], v[218:221], v[210:213], v[70:73]
	v_mfma_f32_16x16x32_bf16 v[66:69], v[226:229], v[210:213], v[66:69]

	s_mov_b32 m0, s59
	v_lshl_add_u64 v[136:137], v[202:203], 0, s[60:61]
	s_barrier
	ds_read_b128 v[158:161], v141 offset:49152
	ds_read_b128 v[162:165], v141 offset:50176
	ds_read_b128 v[166:169], v141 offset:51200
	ds_read_b128 v[170:173], v141 offset:52224
	ds_read_b128 v[178:181], v141 offset:53248
	ds_read_b128 v[182:185], v141 offset:54272
	ds_read_b128 v[186:189], v141 offset:55296
	ds_read_b128 v[210:213], v141 offset:56320
	global_load_lds_dwordx4 v[136:137], off
	v_lshl_add_u64 v[136:137], v[204:205], 0, s[60:61]
	s_mov_b32 m0, s62
	s_nop 0
	global_load_lds_dwordx4 v[136:137], off
	s_barrier
	s_waitcnt lgkmcnt(0)

	s_waitcnt lgkmcnt(0)
	v_mfma_f32_16x16x32_bf16 v[62:65], v[142:145], v[158:161], v[62:65]
	v_mfma_f32_16x16x32_bf16 v[58:61], v[150:153], v[158:161], v[58:61]
	v_mfma_f32_16x16x32_bf16 v[46:49], v[142:145], v[166:169], v[46:49]
	v_mfma_f32_16x16x32_bf16 v[42:45], v[150:153], v[166:169], v[42:45]
	v_mfma_f32_16x16x32_bf16 v[30:33], v[142:145], v[178:181], v[30:33]
	v_mfma_f32_16x16x32_bf16 v[26:29], v[150:153], v[178:181], v[26:29]
	v_mfma_f32_16x16x32_bf16 v[14:17], v[142:145], v[186:189], v[14:17]
	v_mfma_f32_16x16x32_bf16 v[10:13], v[150:153], v[186:189], v[10:13]
	v_mfma_f32_16x16x32_bf16 v[62:65], v[146:149], v[162:165], v[62:65]
	v_mfma_f32_16x16x32_bf16 v[58:61], v[154:157], v[162:165], v[58:61]
	v_mfma_f32_16x16x32_bf16 v[46:49], v[146:149], v[170:173], v[46:49]
	v_mfma_f32_16x16x32_bf16 v[42:45], v[154:157], v[170:173], v[42:45]
	v_mfma_f32_16x16x32_bf16 v[30:33], v[146:149], v[182:185], v[30:33]
	v_mfma_f32_16x16x32_bf16 v[26:29], v[154:157], v[182:185], v[26:29]
	v_mfma_f32_16x16x32_bf16 v[14:17], v[146:149], v[210:213], v[14:17]
	v_mfma_f32_16x16x32_bf16 v[10:13], v[154:157], v[210:213], v[10:13]

	s_barrier
	s_add_u32 s54, s54, 0x40080
	s_addc_u32 s55, s55, 0
	s_add_i32 s56, s56, s40
	v_lshl_add_u64 v[136:137], s[54:55], 0, v[0:1]
	s_mov_b32 m0, s56
	s_nop 0
	global_load_lds_dwordx4 v[136:137], off
	v_lshl_add_u64 v[136:137], s[54:55], 0, v[130:131]
	s_add_i32 m0, s56, 0x2000
	s_nop 0
	global_load_lds_dwordx4 v[136:137], off
	s_waitcnt vmcnt(6)
	s_barrier

	v_mfma_f32_16x16x32_bf16 v[54:57], v[214:217], v[158:161], v[54:57]
	v_mfma_f32_16x16x32_bf16 v[50:53], v[222:225], v[158:161], v[50:53]
	v_mfma_f32_16x16x32_bf16 v[38:41], v[214:217], v[166:169], v[38:41]
	v_mfma_f32_16x16x32_bf16 v[34:37], v[222:225], v[166:169], v[34:37]
	v_mfma_f32_16x16x32_bf16 v[22:25], v[214:217], v[178:181], v[22:25]
	v_mfma_f32_16x16x32_bf16 v[18:21], v[222:225], v[178:181], v[18:21]
	v_mfma_f32_16x16x32_bf16 v[6:9], v[214:217], v[186:189], v[6:9]
	v_mfma_f32_16x16x32_bf16 v[2:5], v[222:225], v[186:189], v[2:5]
	v_mfma_f32_16x16x32_bf16 v[54:57], v[218:221], v[162:165], v[54:57]
	v_mfma_f32_16x16x32_bf16 v[50:53], v[226:229], v[162:165], v[50:53]
	v_mfma_f32_16x16x32_bf16 v[38:41], v[218:221], v[170:173], v[38:41]
	v_mfma_f32_16x16x32_bf16 v[34:37], v[226:229], v[170:173], v[34:37]
	v_mfma_f32_16x16x32_bf16 v[22:25], v[218:221], v[182:185], v[22:25]
	v_mfma_f32_16x16x32_bf16 v[18:21], v[226:229], v[182:185], v[18:21]
	v_mfma_f32_16x16x32_bf16 v[6:9], v[218:221], v[210:213], v[6:9]
	v_mfma_f32_16x16x32_bf16 v[2:5], v[226:229], v[210:213], v[2:5]

	s_add_i32 s23, s23, 2
	s_add_u32 s52, s52, 0x100
	s_addc_u32 s53, s53, 0
	s_add_u32 s90, s90, 0x100
	s_addc_u32 s22, s22, 0
	s_cmp_gt_u32 s23, 13
	s_barrier
	s_cbranch_scc0 .LBB0_960
	v_mul_f32_e32 v143, 0xbfb8aa3b, v126
	v_exp_f32_e32 v143, v143
	v_lshl_or_b32 v144, s64, 7, v140
	v_lshl_add_u32 v142, s65, 8, v138
	v_mov_b64_e32 v[136:137], s[12:13]
	v_add_f32_e32 v143, 1.0, v143
	v_rcp_f32_e32 v148, v143
	v_mul_f32_e32 v143, 0xbfb8aa3b, v127
	v_exp_f32_e32 v143, v143
	v_ashrrev_i32_e32 v145, 31, v144
	v_mad_i64_i32 v[146:147], s[22:23], v142, s89, v[136:137]
	v_add_f32_e32 v143, 1.0, v143
	v_rcp_f32_e32 v149, v143
	s_and_b64 vcc, exec, s[2:3]
	s_mov_b32 s64, s0
	s_mov_b32 s65, s4
	v_pk_mul_f32 v[126:127], v[126:127], v[148:149]
	s_mov_b64 s[54:55], s[18:19]
	v_pk_mul_f32 v[122:123], v[122:123], v[126:127]
	s_mov_b64 s[52:53], s[6:7]
	v_cvt_pk_bf16_f32 v126, v122, v123
	v_mul_f32_e32 v122, 0xbfb8aa3b, v128
	v_mul_f32_e32 v123, 0xbfb8aa3b, v129
	v_exp_f32_e32 v122, v122
	v_exp_f32_e32 v123, v123
	v_add_f32_e32 v122, 1.0, v122
	v_add_f32_e32 v123, 1.0, v123
	v_rcp_f32_e32 v122, v122
	v_rcp_f32_e32 v123, v123
	s_nop 0
	v_pk_mul_f32 v[122:123], v[128:129], v[122:123]
	s_nop 0
	v_pk_mul_f32 v[122:123], v[124:125], v[122:123]
	s_nop 0
	v_cvt_pk_bf16_f32 v127, v122, v123
	v_lshlrev_b64 v[122:123], 1, v[144:145]
	v_lshl_add_u64 v[124:125], v[146:147], 0, v[122:123]
	global_store_dwordx2 v[124:125], v[126:127], off
	v_mul_f32_e32 v126, 0xbfb8aa3b, v118
	v_mul_f32_e32 v127, 0xbfb8aa3b, v119
	v_exp_f32_e32 v126, v126
	v_exp_f32_e32 v127, v127
	v_add_f32_e32 v126, 1.0, v126
	v_add_f32_e32 v127, 1.0, v127
	v_rcp_f32_e32 v126, v126
	v_rcp_f32_e32 v127, v127
	s_nop 0
	v_pk_mul_f32 v[118:119], v[118:119], v[126:127]
	s_nop 0
	v_pk_mul_f32 v[114:115], v[114:115], v[118:119]
	s_nop 0
	v_cvt_pk_bf16_f32 v114, v114, v115
	v_mul_f32_e32 v115, 0xbfb8aa3b, v120
	v_exp_f32_e32 v115, v115
	s_nop 0
	v_add_f32_e32 v115, 1.0, v115
	v_rcp_f32_e32 v118, v115
	v_mul_f32_e32 v115, 0xbfb8aa3b, v121
	v_exp_f32_e32 v115, v115
	s_nop 0
	v_add_f32_e32 v115, 1.0, v115
	v_rcp_f32_e32 v119, v115
	s_nop 0
	v_pk_mul_f32 v[118:119], v[120:121], v[118:119]
	s_nop 0
	v_pk_mul_f32 v[116:117], v[116:117], v[118:119]
	s_nop 0
	v_cvt_pk_bf16_f32 v115, v116, v117
	v_mul_f32_e32 v116, 0xbfb8aa3b, v110
	v_mul_f32_e32 v117, 0xbfb8aa3b, v111
	v_exp_f32_e32 v116, v116
	v_exp_f32_e32 v117, v117
	global_store_dwordx2 v[124:125], v[114:115], off offset:128
	v_or_b32_e32 v114, 16, v142
	v_add_f32_e32 v116, 1.0, v116
	v_add_f32_e32 v117, 1.0, v117
	v_rcp_f32_e32 v116, v116
	v_rcp_f32_e32 v117, v117
	v_mad_i64_i32 v[114:115], s[22:23], v114, s89, v[136:137]
	v_pk_mul_f32 v[110:111], v[110:111], v[116:117]
	s_nop 0
	v_pk_mul_f32 v[106:107], v[106:107], v[110:111]
	s_nop 0
	v_cvt_pk_bf16_f32 v106, v106, v107
	v_mul_f32_e32 v107, 0xbfb8aa3b, v112
	v_exp_f32_e32 v107, v107
	s_nop 0
	v_add_f32_e32 v107, 1.0, v107
	v_rcp_f32_e32 v110, v107
	v_mul_f32_e32 v107, 0xbfb8aa3b, v113
	v_exp_f32_e32 v107, v107
	s_nop 0
	v_add_f32_e32 v107, 1.0, v107
	v_rcp_f32_e32 v111, v107
	s_nop 0
	v_pk_mul_f32 v[110:111], v[112:113], v[110:111]
	s_nop 0
	v_pk_mul_f32 v[108:109], v[108:109], v[110:111]
	s_nop 0
	v_cvt_pk_bf16_f32 v107, v108, v109
	v_lshl_add_u64 v[108:109], v[114:115], 0, v[122:123]
	global_store_dwordx2 v[108:109], v[106:107], off
	v_mul_f32_e32 v106, 0xbfb8aa3b, v102
	v_mul_f32_e32 v107, 0xbfb8aa3b, v103
	v_exp_f32_e32 v106, v106
	v_exp_f32_e32 v107, v107
	v_add_f32_e32 v106, 1.0, v106
	v_add_f32_e32 v107, 1.0, v107
	v_rcp_f32_e32 v106, v106
	v_rcp_f32_e32 v107, v107
	s_nop 0
	v_pk_mul_f32 v[102:103], v[102:103], v[106:107]
	s_nop 0
	v_pk_mul_f32 v[98:99], v[98:99], v[102:103]
	s_nop 0
	v_cvt_pk_bf16_f32 v98, v98, v99
	v_mul_f32_e32 v99, 0xbfb8aa3b, v104
	v_exp_f32_e32 v99, v99
	s_nop 0
	v_add_f32_e32 v99, 1.0, v99
	v_rcp_f32_e32 v102, v99
	v_mul_f32_e32 v99, 0xbfb8aa3b, v105
	v_exp_f32_e32 v99, v99
	s_nop 0
	v_add_f32_e32 v99, 1.0, v99
	v_rcp_f32_e32 v103, v99
	s_nop 0
	v_pk_mul_f32 v[102:103], v[104:105], v[102:103]
	s_nop 0
	v_pk_mul_f32 v[100:101], v[100:101], v[102:103]
	s_nop 0
	v_cvt_pk_bf16_f32 v99, v100, v101
	v_mul_f32_e32 v100, 0xbfb8aa3b, v94
	v_mul_f32_e32 v101, 0xbfb8aa3b, v95
	v_exp_f32_e32 v100, v100
	v_exp_f32_e32 v101, v101
	global_store_dwordx2 v[108:109], v[98:99], off offset:128
	v_or_b32_e32 v98, 32, v142
	v_add_f32_e32 v100, 1.0, v100
	v_add_f32_e32 v101, 1.0, v101
	v_rcp_f32_e32 v100, v100
	v_rcp_f32_e32 v101, v101
	v_mad_i64_i32 v[98:99], s[22:23], v98, s89, v[136:137]
	v_pk_mul_f32 v[94:95], v[94:95], v[100:101]
	s_nop 0
	v_pk_mul_f32 v[90:91], v[90:91], v[94:95]
	s_nop 0
	v_cvt_pk_bf16_f32 v90, v90, v91
	v_mul_f32_e32 v91, 0xbfb8aa3b, v96
	v_exp_f32_e32 v91, v91
	s_nop 0
	v_add_f32_e32 v91, 1.0, v91
	v_rcp_f32_e32 v94, v91
	v_mul_f32_e32 v91, 0xbfb8aa3b, v97
	v_exp_f32_e32 v91, v91
	s_nop 0
	v_add_f32_e32 v91, 1.0, v91
	v_rcp_f32_e32 v95, v91
	s_nop 0
	v_pk_mul_f32 v[94:95], v[96:97], v[94:95]
	s_nop 0
	v_pk_mul_f32 v[92:93], v[92:93], v[94:95]
	s_nop 0
	v_cvt_pk_bf16_f32 v91, v92, v93
	v_lshl_add_u64 v[92:93], v[98:99], 0, v[122:123]
	global_store_dwordx2 v[92:93], v[90:91], off
	v_mul_f32_e32 v90, 0xbfb8aa3b, v86
	v_mul_f32_e32 v91, 0xbfb8aa3b, v87
	v_exp_f32_e32 v90, v90
	v_exp_f32_e32 v91, v91
	v_add_f32_e32 v90, 1.0, v90
	v_add_f32_e32 v91, 1.0, v91
	v_rcp_f32_e32 v90, v90
	v_rcp_f32_e32 v91, v91
	s_nop 0
	v_pk_mul_f32 v[86:87], v[86:87], v[90:91]
	s_nop 0
	v_pk_mul_f32 v[82:83], v[82:83], v[86:87]
	s_nop 0
	v_cvt_pk_bf16_f32 v82, v82, v83
	v_mul_f32_e32 v83, 0xbfb8aa3b, v88
	v_exp_f32_e32 v83, v83
	s_nop 0
	v_add_f32_e32 v83, 1.0, v83
	v_rcp_f32_e32 v86, v83
	v_mul_f32_e32 v83, 0xbfb8aa3b, v89
	v_exp_f32_e32 v83, v83
	s_nop 0
	v_add_f32_e32 v83, 1.0, v83
	v_rcp_f32_e32 v87, v83
	s_nop 0
	v_pk_mul_f32 v[86:87], v[88:89], v[86:87]
	s_nop 0
	v_pk_mul_f32 v[84:85], v[84:85], v[86:87]
	s_nop 0
	v_cvt_pk_bf16_f32 v83, v84, v85
	v_mul_f32_e32 v84, 0xbfb8aa3b, v78
	v_mul_f32_e32 v85, 0xbfb8aa3b, v79
	v_exp_f32_e32 v84, v84
	v_exp_f32_e32 v85, v85
	global_store_dwordx2 v[92:93], v[82:83], off offset:128
	v_or_b32_e32 v82, 48, v142
	v_add_f32_e32 v84, 1.0, v84
	v_add_f32_e32 v85, 1.0, v85
	v_rcp_f32_e32 v84, v84
	v_rcp_f32_e32 v85, v85
	v_mad_i64_i32 v[82:83], s[22:23], v82, s89, v[136:137]
	v_pk_mul_f32 v[78:79], v[78:79], v[84:85]
	s_nop 0
	v_pk_mul_f32 v[74:75], v[74:75], v[78:79]
	s_nop 0
	v_cvt_pk_bf16_f32 v74, v74, v75
	v_mul_f32_e32 v75, 0xbfb8aa3b, v80
	v_exp_f32_e32 v75, v75
	s_nop 0
	v_add_f32_e32 v75, 1.0, v75
	v_rcp_f32_e32 v78, v75
	v_mul_f32_e32 v75, 0xbfb8aa3b, v81
	v_exp_f32_e32 v75, v75
	s_nop 0
	v_add_f32_e32 v75, 1.0, v75
	v_rcp_f32_e32 v79, v75
	s_nop 0
	v_pk_mul_f32 v[78:79], v[80:81], v[78:79]
	s_nop 0
	v_pk_mul_f32 v[76:77], v[76:77], v[78:79]
	s_nop 0
	v_cvt_pk_bf16_f32 v75, v76, v77
	v_lshl_add_u64 v[76:77], v[82:83], 0, v[122:123]
	global_store_dwordx2 v[76:77], v[74:75], off
	v_mul_f32_e32 v74, 0xbfb8aa3b, v70
	v_mul_f32_e32 v75, 0xbfb8aa3b, v71
	v_exp_f32_e32 v74, v74
	v_exp_f32_e32 v75, v75
	v_add_f32_e32 v74, 1.0, v74
	v_add_f32_e32 v75, 1.0, v75
	v_rcp_f32_e32 v74, v74
	v_rcp_f32_e32 v75, v75
	s_nop 0
	v_pk_mul_f32 v[70:71], v[70:71], v[74:75]
	s_nop 0
	v_pk_mul_f32 v[66:67], v[66:67], v[70:71]
	s_nop 0
	v_cvt_pk_bf16_f32 v66, v66, v67
	v_mul_f32_e32 v67, 0xbfb8aa3b, v72
	v_exp_f32_e32 v67, v67
	s_nop 0
	v_add_f32_e32 v67, 1.0, v67
	v_rcp_f32_e32 v70, v67
	v_mul_f32_e32 v67, 0xbfb8aa3b, v73
	v_exp_f32_e32 v67, v67
	s_nop 0
	v_add_f32_e32 v67, 1.0, v67
	v_rcp_f32_e32 v71, v67
	s_nop 0
	v_pk_mul_f32 v[70:71], v[72:73], v[70:71]
	s_nop 0
	v_pk_mul_f32 v[68:69], v[68:69], v[70:71]
	s_nop 0
	v_cvt_pk_bf16_f32 v67, v68, v69
	v_mul_f32_e32 v68, 0xbfb8aa3b, v62
	v_mul_f32_e32 v69, 0xbfb8aa3b, v63
	v_exp_f32_e32 v68, v68
	v_exp_f32_e32 v69, v69
	global_store_dwordx2 v[76:77], v[66:67], off offset:128
	v_add_u32_e32 v66, 0x80, v142
	v_add_f32_e32 v68, 1.0, v68
	v_add_f32_e32 v69, 1.0, v69
	v_rcp_f32_e32 v68, v68
	v_rcp_f32_e32 v69, v69
	v_mad_i64_i32 v[66:67], s[22:23], v66, s89, v[136:137]
	v_pk_mul_f32 v[62:63], v[62:63], v[68:69]
	s_nop 0
	v_pk_mul_f32 v[58:59], v[58:59], v[62:63]
	s_nop 0
	v_cvt_pk_bf16_f32 v58, v58, v59
	v_mul_f32_e32 v59, 0xbfb8aa3b, v64
	v_exp_f32_e32 v59, v59
	s_nop 0
	v_add_f32_e32 v59, 1.0, v59
	v_rcp_f32_e32 v62, v59
	v_mul_f32_e32 v59, 0xbfb8aa3b, v65
	v_exp_f32_e32 v59, v59
	s_nop 0
	v_add_f32_e32 v59, 1.0, v59
	v_rcp_f32_e32 v63, v59
	s_nop 0
	v_pk_mul_f32 v[62:63], v[64:65], v[62:63]
	s_nop 0
	v_pk_mul_f32 v[60:61], v[60:61], v[62:63]
	s_nop 0
	v_cvt_pk_bf16_f32 v59, v60, v61
	v_lshl_add_u64 v[60:61], v[66:67], 0, v[122:123]
	global_store_dwordx2 v[60:61], v[58:59], off
	v_mul_f32_e32 v58, 0xbfb8aa3b, v54
	v_mul_f32_e32 v59, 0xbfb8aa3b, v55
	v_exp_f32_e32 v58, v58
	v_exp_f32_e32 v59, v59
	v_add_f32_e32 v58, 1.0, v58
	v_add_f32_e32 v59, 1.0, v59
	v_rcp_f32_e32 v58, v58
	v_rcp_f32_e32 v59, v59
	s_nop 0
	v_pk_mul_f32 v[54:55], v[54:55], v[58:59]
	s_nop 0
	v_pk_mul_f32 v[50:51], v[50:51], v[54:55]
	s_nop 0
	v_cvt_pk_bf16_f32 v50, v50, v51
	v_mul_f32_e32 v51, 0xbfb8aa3b, v56
	v_exp_f32_e32 v51, v51
	s_nop 0
	v_add_f32_e32 v51, 1.0, v51
	v_rcp_f32_e32 v54, v51
	v_mul_f32_e32 v51, 0xbfb8aa3b, v57
	v_exp_f32_e32 v51, v51
	s_nop 0
	v_add_f32_e32 v51, 1.0, v51
	v_rcp_f32_e32 v55, v51
	s_nop 0
	v_pk_mul_f32 v[54:55], v[56:57], v[54:55]
	s_nop 0
	v_pk_mul_f32 v[52:53], v[52:53], v[54:55]
	s_nop 0
	v_cvt_pk_bf16_f32 v51, v52, v53
	v_mul_f32_e32 v52, 0xbfb8aa3b, v46
	v_mul_f32_e32 v53, 0xbfb8aa3b, v47
	v_exp_f32_e32 v52, v52
	v_exp_f32_e32 v53, v53
	global_store_dwordx2 v[60:61], v[50:51], off offset:128
	v_add_u32_e32 v50, 0x90, v142
	v_add_f32_e32 v52, 1.0, v52
	v_add_f32_e32 v53, 1.0, v53
	v_rcp_f32_e32 v52, v52
	v_rcp_f32_e32 v53, v53
	v_mad_i64_i32 v[50:51], s[22:23], v50, s89, v[136:137]
	v_pk_mul_f32 v[46:47], v[46:47], v[52:53]
	s_nop 0
	v_pk_mul_f32 v[42:43], v[42:43], v[46:47]
	s_nop 0
	v_cvt_pk_bf16_f32 v42, v42, v43
	v_mul_f32_e32 v43, 0xbfb8aa3b, v48
	v_exp_f32_e32 v43, v43
	s_nop 0
	v_add_f32_e32 v43, 1.0, v43
	v_rcp_f32_e32 v46, v43
	v_mul_f32_e32 v43, 0xbfb8aa3b, v49
	v_exp_f32_e32 v43, v43
	s_nop 0
	v_add_f32_e32 v43, 1.0, v43
	v_rcp_f32_e32 v47, v43
	s_nop 0
	v_pk_mul_f32 v[46:47], v[48:49], v[46:47]
	s_nop 0
	v_pk_mul_f32 v[44:45], v[44:45], v[46:47]
	s_nop 0
	v_cvt_pk_bf16_f32 v43, v44, v45
	v_lshl_add_u64 v[44:45], v[50:51], 0, v[122:123]
	global_store_dwordx2 v[44:45], v[42:43], off
	v_mul_f32_e32 v42, 0xbfb8aa3b, v38
	v_mul_f32_e32 v43, 0xbfb8aa3b, v39
	v_exp_f32_e32 v42, v42
	v_exp_f32_e32 v43, v43
	v_add_f32_e32 v42, 1.0, v42
	v_add_f32_e32 v43, 1.0, v43
	v_rcp_f32_e32 v42, v42
	v_rcp_f32_e32 v43, v43
	s_nop 0
	v_pk_mul_f32 v[38:39], v[38:39], v[42:43]
	s_nop 0
	v_pk_mul_f32 v[34:35], v[34:35], v[38:39]
	s_nop 0
	v_cvt_pk_bf16_f32 v34, v34, v35
	v_mul_f32_e32 v35, 0xbfb8aa3b, v40
	v_exp_f32_e32 v35, v35
	s_nop 0
	v_add_f32_e32 v35, 1.0, v35
	v_rcp_f32_e32 v38, v35
	v_mul_f32_e32 v35, 0xbfb8aa3b, v41
	v_exp_f32_e32 v35, v35
	s_nop 0
	v_add_f32_e32 v35, 1.0, v35
	v_rcp_f32_e32 v39, v35
	s_nop 0
	v_pk_mul_f32 v[38:39], v[40:41], v[38:39]
	s_nop 0
	v_pk_mul_f32 v[36:37], v[36:37], v[38:39]
	s_nop 0
	v_cvt_pk_bf16_f32 v35, v36, v37
	v_mul_f32_e32 v36, 0xbfb8aa3b, v30
	v_mul_f32_e32 v37, 0xbfb8aa3b, v31
	v_exp_f32_e32 v36, v36
	v_exp_f32_e32 v37, v37
	global_store_dwordx2 v[44:45], v[34:35], off offset:128
	v_add_u32_e32 v34, 0xa0, v142
	v_add_f32_e32 v36, 1.0, v36
	v_add_f32_e32 v37, 1.0, v37
	v_rcp_f32_e32 v36, v36
	v_rcp_f32_e32 v37, v37
	v_mad_i64_i32 v[34:35], s[22:23], v34, s89, v[136:137]
	v_pk_mul_f32 v[30:31], v[30:31], v[36:37]
	s_nop 0
	v_pk_mul_f32 v[26:27], v[26:27], v[30:31]
	s_nop 0
	v_cvt_pk_bf16_f32 v26, v26, v27
	v_mul_f32_e32 v27, 0xbfb8aa3b, v32
	v_exp_f32_e32 v27, v27
	s_nop 0
	v_add_f32_e32 v27, 1.0, v27
	v_rcp_f32_e32 v30, v27
	v_mul_f32_e32 v27, 0xbfb8aa3b, v33
	v_exp_f32_e32 v27, v27
	s_nop 0
	v_add_f32_e32 v27, 1.0, v27
	v_rcp_f32_e32 v31, v27
	s_nop 0
	v_pk_mul_f32 v[30:31], v[32:33], v[30:31]
	s_nop 0
	v_pk_mul_f32 v[28:29], v[28:29], v[30:31]
	s_nop 0
	v_cvt_pk_bf16_f32 v27, v28, v29
	v_lshl_add_u64 v[28:29], v[34:35], 0, v[122:123]
	global_store_dwordx2 v[28:29], v[26:27], off
	v_mul_f32_e32 v26, 0xbfb8aa3b, v22
	v_mul_f32_e32 v27, 0xbfb8aa3b, v23
	v_exp_f32_e32 v26, v26
	v_exp_f32_e32 v27, v27
	v_add_f32_e32 v26, 1.0, v26
	v_add_f32_e32 v27, 1.0, v27
	v_rcp_f32_e32 v26, v26
	v_rcp_f32_e32 v27, v27
	s_nop 0
	v_pk_mul_f32 v[22:23], v[22:23], v[26:27]
	s_nop 0
	v_pk_mul_f32 v[18:19], v[18:19], v[22:23]
	s_nop 0
	v_cvt_pk_bf16_f32 v18, v18, v19
	v_mul_f32_e32 v19, 0xbfb8aa3b, v24
	v_exp_f32_e32 v19, v19
	s_nop 0
	v_add_f32_e32 v19, 1.0, v19
	v_rcp_f32_e32 v22, v19
	v_mul_f32_e32 v19, 0xbfb8aa3b, v25
	v_exp_f32_e32 v19, v19
	s_nop 0
	v_add_f32_e32 v19, 1.0, v19
	v_rcp_f32_e32 v23, v19
	s_nop 0
	v_pk_mul_f32 v[22:23], v[24:25], v[22:23]
	s_nop 0
	v_pk_mul_f32 v[20:21], v[20:21], v[22:23]
	s_nop 0
	v_cvt_pk_bf16_f32 v19, v20, v21
	v_mul_f32_e32 v20, 0xbfb8aa3b, v14
	v_mul_f32_e32 v21, 0xbfb8aa3b, v15
	v_exp_f32_e32 v20, v20
	v_exp_f32_e32 v21, v21
	global_store_dwordx2 v[28:29], v[18:19], off offset:128
	v_add_u32_e32 v18, 0xb0, v142
	v_add_f32_e32 v20, 1.0, v20
	v_add_f32_e32 v21, 1.0, v21
	v_rcp_f32_e32 v20, v20
	v_rcp_f32_e32 v21, v21
	v_mad_i64_i32 v[18:19], s[22:23], v18, s89, v[136:137]
	v_pk_mul_f32 v[14:15], v[14:15], v[20:21]
	s_nop 0
	v_pk_mul_f32 v[10:11], v[10:11], v[14:15]
	s_nop 0
	v_cvt_pk_bf16_f32 v10, v10, v11
	v_mul_f32_e32 v11, 0xbfb8aa3b, v16
	v_exp_f32_e32 v11, v11
	s_nop 0
	v_add_f32_e32 v11, 1.0, v11
	v_rcp_f32_e32 v14, v11
	v_mul_f32_e32 v11, 0xbfb8aa3b, v17
	v_exp_f32_e32 v11, v11
	s_nop 0
	v_add_f32_e32 v11, 1.0, v11
	v_rcp_f32_e32 v15, v11
	s_nop 0
	v_pk_mul_f32 v[14:15], v[16:17], v[14:15]
	s_nop 0
	v_pk_mul_f32 v[12:13], v[12:13], v[14:15]
	s_nop 0
	v_cvt_pk_bf16_f32 v11, v12, v13
	v_lshl_add_u64 v[12:13], v[18:19], 0, v[122:123]
	global_store_dwordx2 v[12:13], v[10:11], off
	v_mul_f32_e32 v10, 0xbfb8aa3b, v6
	v_mul_f32_e32 v11, 0xbfb8aa3b, v7
	v_exp_f32_e32 v10, v10
	v_exp_f32_e32 v11, v11
	v_add_f32_e32 v10, 1.0, v10
	v_add_f32_e32 v11, 1.0, v11
	v_rcp_f32_e32 v10, v10
	v_rcp_f32_e32 v11, v11
	s_nop 0
	v_pk_mul_f32 v[6:7], v[6:7], v[10:11]
	s_nop 0
	v_pk_mul_f32 v[2:3], v[2:3], v[6:7]
	s_nop 0
	v_cvt_pk_bf16_f32 v2, v2, v3
	v_mul_f32_e32 v3, 0xbfb8aa3b, v8
	v_exp_f32_e32 v3, v3
	s_nop 0
	v_add_f32_e32 v3, 1.0, v3
	v_rcp_f32_e32 v6, v3
	v_mul_f32_e32 v3, 0xbfb8aa3b, v9
	v_exp_f32_e32 v3, v3
	s_nop 0
	v_add_f32_e32 v3, 1.0, v3
	v_rcp_f32_e32 v7, v3
	s_nop 0
	v_pk_mul_f32 v[6:7], v[8:9], v[6:7]
	s_nop 0
	v_pk_mul_f32 v[4:5], v[4:5], v[6:7]
	s_nop 0
	v_cvt_pk_bf16_f32 v3, v4, v5
	global_store_dwordx2 v[12:13], v[2:3], off offset:128
	s_cbranch_vccz .LBB0_957
	s_waitcnt vmcnt(0)
	v_readlane_b32 s64, v254, 62
	s_cmpk_gt_u32 s14, 0xff
	v_readlane_b32 s65, v254, 63
	s_cbranch_scc1 .LBB0_964
	s_barrier

.LBB0_1049:
	s_add_u32 s52, s18, 0x100
	s_addc_u32 s53, s19, 0
	s_add_i32 s68, 0, 0x10000
	v_add_u32_e32 v78, s68, v165
	ds_read_b128 v[66:69], v78
	ds_read_b128 v[70:73], v78 offset:1024
	ds_read_b128 v[74:77], v78 offset:2048
	ds_read_b128 v[78:81], v78 offset:3072
	s_cmp_eq_u32 s94, 40
	s_cselect_b32 s57, s5, s53
	s_cselect_b32 s56, s4, s52
	s_cselect_b32 s55, s1, s23
	s_cselect_b32 s54, s0, s22
	v_lshl_add_u64 v[172:173], s[18:19], 0, v[148:149]
	s_add_i32 m0, s41, 0xc000
	ds_read_b128 v[152:155], v167
	ds_read_b128 v[156:159], v167 offset:1024
	ds_read_b128 v[160:163], v167 offset:2048
	ds_read_b128 v[168:171], v167 offset:3072
	ds_read_b128 v[178:181], v167 offset:4096
	ds_read_b128 v[182:185], v167 offset:5120
	ds_read_b128 v[186:189], v167 offset:6144
	ds_read_b128 v[202:205], v167 offset:7168
	global_load_lds_dwordx4 v[172:173], off
	v_lshl_add_u64 v[172:173], s[18:19], 0, v[150:151]
	s_add_i32 m0, s41, 0xe000
	s_nop 0
	global_load_lds_dwordx4 v[172:173], off
	s_waitcnt lgkmcnt(8)
	s_barrier
	s_waitcnt lgkmcnt(0)

	s_waitcnt lgkmcnt(0)
	v_mfma_f32_16x16x32_bf16 v[142:145], v[66:69], v[152:155], v[142:145]
	v_mfma_f32_16x16x32_bf16 v[138:141], v[74:77], v[152:155], v[138:141]
	v_mfma_f32_16x16x32_bf16 v[134:137], v[66:69], v[160:163], v[134:137]
	v_mfma_f32_16x16x32_bf16 v[130:133], v[74:77], v[160:163], v[130:133]
	v_mfma_f32_16x16x32_bf16 v[122:125], v[66:69], v[178:181], v[122:125]
	v_mfma_f32_16x16x32_bf16 v[114:117], v[74:77], v[178:181], v[114:117]
	v_mfma_f32_16x16x32_bf16 v[106:109], v[66:69], v[186:189], v[106:109]
	v_mfma_f32_16x16x32_bf16 v[98:101], v[74:77], v[186:189], v[98:101]
	v_mfma_f32_16x16x32_bf16 v[142:145], v[70:73], v[156:159], v[142:145]
	v_mfma_f32_16x16x32_bf16 v[138:141], v[78:81], v[156:159], v[138:141]
	v_mfma_f32_16x16x32_bf16 v[134:137], v[70:73], v[168:171], v[134:137]
	v_mfma_f32_16x16x32_bf16 v[130:133], v[78:81], v[168:171], v[130:133]
	v_mfma_f32_16x16x32_bf16 v[122:125], v[70:73], v[182:185], v[122:125]
	v_mfma_f32_16x16x32_bf16 v[114:117], v[78:81], v[182:185], v[114:117]
	v_mfma_f32_16x16x32_bf16 v[106:109], v[70:73], v[202:205], v[106:109]
	v_mfma_f32_16x16x32_bf16 v[98:101], v[78:81], v[202:205], v[98:101]

	s_barrier
	s_add_i32 s69, 0, 0x14000
	v_add_u32_e32 v172, s69, v165
	s_add_i32 s18, s68, s40
	ds_read_b128 v[210:213], v172
	ds_read_b128 v[214:217], v172 offset:1024
	ds_read_b128 v[218:221], v172 offset:2048
	ds_read_b128 v[222:225], v172 offset:3072
	v_lshl_add_u64 v[172:173], s[54:55], 0, v[0:1]
	s_mov_b32 m0, s18
	v_lshl_add_u64 v[190:191], s[54:55], 0, v[146:147]
	global_load_lds_dwordx4 v[172:173], off
	s_add_i32 m0, s18, 0x2000
	s_nop 0
	global_load_lds_dwordx4 v[190:191], off
	s_barrier
	s_waitcnt lgkmcnt(0)

	s_waitcnt lgkmcnt(0)
	v_mfma_f32_16x16x32_bf16 v[126:129], v[210:213], v[152:155], v[126:129]
	v_mfma_f32_16x16x32_bf16 v[118:121], v[218:221], v[152:155], v[118:121]
	v_mfma_f32_16x16x32_bf16 v[110:113], v[210:213], v[160:163], v[110:113]
	v_mfma_f32_16x16x32_bf16 v[102:105], v[218:221], v[160:163], v[102:105]
	v_mfma_f32_16x16x32_bf16 v[94:97], v[210:213], v[178:181], v[94:97]
	v_mfma_f32_16x16x32_bf16 v[90:93], v[218:221], v[178:181], v[90:93]
	v_mfma_f32_16x16x32_bf16 v[86:89], v[210:213], v[186:189], v[86:89]
	v_mfma_f32_16x16x32_bf16 v[82:85], v[218:221], v[186:189], v[82:85]
	v_mfma_f32_16x16x32_bf16 v[126:129], v[214:217], v[156:159], v[126:129]
	v_mfma_f32_16x16x32_bf16 v[118:121], v[222:225], v[156:159], v[118:121]
	v_mfma_f32_16x16x32_bf16 v[110:113], v[214:217], v[168:171], v[110:113]
	v_mfma_f32_16x16x32_bf16 v[102:105], v[222:225], v[168:171], v[102:105]
	v_mfma_f32_16x16x32_bf16 v[94:97], v[214:217], v[182:185], v[94:97]
	v_mfma_f32_16x16x32_bf16 v[90:93], v[222:225], v[182:185], v[90:93]
	v_mfma_f32_16x16x32_bf16 v[86:89], v[214:217], v[202:205], v[86:89]
	v_mfma_f32_16x16x32_bf16 v[82:85], v[222:225], v[202:205], v[82:85]

	s_mov_b32 m0, s41
	v_lshl_add_u64 v[226:227], s[56:57], 0, v[0:1]
	s_barrier
	ds_read_b128 v[152:155], v167 offset:16384
	ds_read_b128 v[156:159], v167 offset:17408
	ds_read_b128 v[160:163], v167 offset:18432
	ds_read_b128 v[168:171], v167 offset:19456
	ds_read_b128 v[178:181], v167 offset:20480
	ds_read_b128 v[182:185], v167 offset:21504
	ds_read_b128 v[186:189], v167 offset:22528
	ds_read_b128 v[202:205], v167 offset:23552
	global_load_lds_dwordx4 v[226:227], off
	v_lshl_add_u64 v[228:229], s[56:57], 0, v[146:147]
	s_mov_b32 m0, s42
	s_nop 0
	global_load_lds_dwordx4 v[228:229], off
	s_barrier
	s_waitcnt lgkmcnt(0)

	s_waitcnt lgkmcnt(0)
	v_mfma_f32_16x16x32_bf16 v[62:65], v[66:69], v[152:155], v[62:65]
	v_mfma_f32_16x16x32_bf16 v[58:61], v[74:77], v[152:155], v[58:61]
	v_mfma_f32_16x16x32_bf16 v[54:57], v[66:69], v[160:163], v[54:57]
	v_mfma_f32_16x16x32_bf16 v[46:49], v[74:77], v[160:163], v[46:49]
	v_mfma_f32_16x16x32_bf16 v[38:41], v[66:69], v[178:181], v[38:41]
	v_mfma_f32_16x16x32_bf16 v[30:33], v[74:77], v[178:181], v[30:33]
	v_mfma_f32_16x16x32_bf16 v[22:25], v[66:69], v[186:189], v[22:25]
	v_mfma_f32_16x16x32_bf16 v[14:17], v[74:77], v[186:189], v[14:17]
	v_mfma_f32_16x16x32_bf16 v[62:65], v[70:73], v[156:159], v[62:65]
	v_mfma_f32_16x16x32_bf16 v[58:61], v[78:81], v[156:159], v[58:61]
	v_mfma_f32_16x16x32_bf16 v[54:57], v[70:73], v[168:171], v[54:57]
	v_mfma_f32_16x16x32_bf16 v[46:49], v[78:81], v[168:171], v[46:49]
	v_mfma_f32_16x16x32_bf16 v[38:41], v[70:73], v[182:185], v[38:41]
	v_mfma_f32_16x16x32_bf16 v[30:33], v[78:81], v[182:185], v[30:33]
	v_mfma_f32_16x16x32_bf16 v[22:25], v[70:73], v[202:205], v[22:25]
	v_mfma_f32_16x16x32_bf16 v[14:17], v[78:81], v[202:205], v[14:17]

	s_barrier
	s_add_u32 s18, s54, 0xb0000
	s_addc_u32 s19, s55, 0
	s_add_i32 s68, s69, s40
	v_lshl_add_u64 v[66:67], s[18:19], 0, v[0:1]
	s_mov_b32 m0, s68
	s_nop 0
	global_load_lds_dwordx4 v[66:67], off
	v_lshl_add_u64 v[66:67], s[18:19], 0, v[146:147]
	s_add_i32 m0, s68, 0x2000
	s_nop 0
	global_load_lds_dwordx4 v[66:67], off
	s_waitcnt vmcnt(6)
	s_barrier

	v_mfma_f32_16x16x32_bf16 v[50:53], v[210:213], v[152:155], v[50:53]
	v_mfma_f32_16x16x32_bf16 v[42:45], v[218:221], v[152:155], v[42:45]
	v_mfma_f32_16x16x32_bf16 v[34:37], v[210:213], v[160:163], v[34:37]
	v_mfma_f32_16x16x32_bf16 v[26:29], v[218:221], v[160:163], v[26:29]
	v_mfma_f32_16x16x32_bf16 v[18:21], v[210:213], v[178:181], v[18:21]
	v_mfma_f32_16x16x32_bf16 v[10:13], v[218:221], v[178:181], v[10:13]
	v_mfma_f32_16x16x32_bf16 v[6:9], v[210:213], v[186:189], v[6:9]
	v_mfma_f32_16x16x32_bf16 v[2:5], v[218:221], v[186:189], v[2:5]
	v_mfma_f32_16x16x32_bf16 v[50:53], v[214:217], v[156:159], v[50:53]
	v_mfma_f32_16x16x32_bf16 v[42:45], v[222:225], v[156:159], v[42:45]
	v_mfma_f32_16x16x32_bf16 v[34:37], v[214:217], v[168:171], v[34:37]
	v_mfma_f32_16x16x32_bf16 v[26:29], v[222:225], v[168:171], v[26:29]
	v_mfma_f32_16x16x32_bf16 v[18:21], v[214:217], v[182:185], v[18:21]
	v_mfma_f32_16x16x32_bf16 v[10:13], v[222:225], v[182:185], v[10:13]
	v_mfma_f32_16x16x32_bf16 v[6:9], v[214:217], v[202:205], v[6:9]
	v_mfma_f32_16x16x32_bf16 v[2:5], v[222:225], v[202:205], v[2:5]

	s_add_i32 s68, 0, 0x18000
	v_add_u32_e32 v78, s68, v165
	s_barrier
	ds_read_b128 v[66:69], v78
	ds_read_b128 v[70:73], v78 offset:1024
	ds_read_b128 v[74:77], v78 offset:2048
	ds_read_b128 v[78:81], v78 offset:3072
	s_add_u32 s18, s56, 0xb0000
	s_addc_u32 s19, s57, 0
	s_mov_b32 m0, s43
	v_lshl_add_u64 v[210:211], s[18:19], 0, v[0:1]
	ds_read_b128 v[152:155], v167 offset:32768
	ds_read_b128 v[156:159], v167 offset:33792
	ds_read_b128 v[160:163], v167 offset:34816
	ds_read_b128 v[168:171], v167 offset:35840
	ds_read_b128 v[178:181], v167 offset:36864
	ds_read_b128 v[182:185], v167 offset:37888
	ds_read_b128 v[186:189], v167 offset:38912
	ds_read_b128 v[202:205], v167 offset:39936
	global_load_lds_dwordx4 v[210:211], off
	v_lshl_add_u64 v[210:211], s[18:19], 0, v[146:147]
	s_mov_b32 m0, s58
	s_nop 0
	global_load_lds_dwordx4 v[210:211], off
	s_waitcnt lgkmcnt(8)
	s_barrier
	s_waitcnt lgkmcnt(0)

	s_waitcnt lgkmcnt(0)
	v_mfma_f32_16x16x32_bf16 v[142:145], v[66:69], v[152:155], v[142:145]
	v_mfma_f32_16x16x32_bf16 v[138:141], v[74:77], v[152:155], v[138:141]
	v_mfma_f32_16x16x32_bf16 v[134:137], v[66:69], v[160:163], v[134:137]
	v_mfma_f32_16x16x32_bf16 v[130:133], v[74:77], v[160:163], v[130:133]
	v_mfma_f32_16x16x32_bf16 v[122:125], v[66:69], v[178:181], v[122:125]
	v_mfma_f32_16x16x32_bf16 v[114:117], v[74:77], v[178:181], v[114:117]
	v_mfma_f32_16x16x32_bf16 v[106:109], v[66:69], v[186:189], v[106:109]
	v_mfma_f32_16x16x32_bf16 v[98:101], v[74:77], v[186:189], v[98:101]
	v_mfma_f32_16x16x32_bf16 v[142:145], v[70:73], v[156:159], v[142:145]
	v_mfma_f32_16x16x32_bf16 v[138:141], v[78:81], v[156:159], v[138:141]
	v_mfma_f32_16x16x32_bf16 v[134:137], v[70:73], v[168:171], v[134:137]
	v_mfma_f32_16x16x32_bf16 v[130:133], v[78:81], v[168:171], v[130:133]
	v_mfma_f32_16x16x32_bf16 v[122:125], v[70:73], v[182:185], v[122:125]
	v_mfma_f32_16x16x32_bf16 v[114:117], v[78:81], v[182:185], v[114:117]
	v_mfma_f32_16x16x32_bf16 v[106:109], v[70:73], v[202:205], v[106:109]
	v_mfma_f32_16x16x32_bf16 v[98:101], v[78:81], v[202:205], v[98:101]

	s_barrier
	s_add_i32 s56, 0, 0x1c000
	s_add_i32 s18, s68, s40
	v_add_u32_e32 v209, s56, v165
	v_lshl_add_u64 v[172:173], v[172:173], 0, s[60:61]
	s_mov_b32 m0, s18
	ds_read_b128 v[210:213], v209
	ds_read_b128 v[214:217], v209 offset:1024
	ds_read_b128 v[218:221], v209 offset:2048
	ds_read_b128 v[222:225], v209 offset:3072
	global_load_lds_dwordx4 v[172:173], off
	v_lshl_add_u64 v[172:173], v[190:191], 0, s[60:61]
	s_add_i32 m0, s18, 0x2000
	s_nop 0
	global_load_lds_dwordx4 v[172:173], off
	s_barrier
	s_waitcnt lgkmcnt(0)

	s_waitcnt lgkmcnt(0)
	v_mfma_f32_16x16x32_bf16 v[126:129], v[210:213], v[152:155], v[126:129]
	v_mfma_f32_16x16x32_bf16 v[118:121], v[218:221], v[152:155], v[118:121]
	v_mfma_f32_16x16x32_bf16 v[110:113], v[210:213], v[160:163], v[110:113]
	v_mfma_f32_16x16x32_bf16 v[102:105], v[218:221], v[160:163], v[102:105]
	v_mfma_f32_16x16x32_bf16 v[94:97], v[210:213], v[178:181], v[94:97]
	v_mfma_f32_16x16x32_bf16 v[90:93], v[218:221], v[178:181], v[90:93]
	v_mfma_f32_16x16x32_bf16 v[86:89], v[210:213], v[186:189], v[86:89]
	v_mfma_f32_16x16x32_bf16 v[82:85], v[218:221], v[186:189], v[82:85]
	v_mfma_f32_16x16x32_bf16 v[126:129], v[214:217], v[156:159], v[126:129]
	v_mfma_f32_16x16x32_bf16 v[118:121], v[222:225], v[156:159], v[118:121]
	v_mfma_f32_16x16x32_bf16 v[110:113], v[214:217], v[168:171], v[110:113]
	v_mfma_f32_16x16x32_bf16 v[102:105], v[222:225], v[168:171], v[102:105]
	v_mfma_f32_16x16x32_bf16 v[94:97], v[214:217], v[182:185], v[94:97]
	v_mfma_f32_16x16x32_bf16 v[90:93], v[222:225], v[182:185], v[90:93]
	v_mfma_f32_16x16x32_bf16 v[86:89], v[214:217], v[202:205], v[86:89]
	v_mfma_f32_16x16x32_bf16 v[82:85], v[222:225], v[202:205], v[82:85]

	s_mov_b32 m0, s63
	v_lshl_add_u64 v[172:173], v[226:227], 0, s[60:61]
	s_barrier
	ds_read_b128 v[152:155], v167 offset:49152
	ds_read_b128 v[156:159], v167 offset:50176
	ds_read_b128 v[160:163], v167 offset:51200
	ds_read_b128 v[168:171], v167 offset:52224
	ds_read_b128 v[178:181], v167 offset:53248
	ds_read_b128 v[182:185], v167 offset:54272
	ds_read_b128 v[186:189], v167 offset:55296
	ds_read_b128 v[202:205], v167 offset:56320
	global_load_lds_dwordx4 v[172:173], off
	v_lshl_add_u64 v[172:173], v[228:229], 0, s[60:61]
	s_mov_b32 m0, s64
	s_nop 0
	global_load_lds_dwordx4 v[172:173], off
	s_barrier
	s_waitcnt lgkmcnt(0)

	s_waitcnt lgkmcnt(0)
	v_mfma_f32_16x16x32_bf16 v[62:65], v[66:69], v[152:155], v[62:65]
	v_mfma_f32_16x16x32_bf16 v[58:61], v[74:77], v[152:155], v[58:61]
	v_mfma_f32_16x16x32_bf16 v[54:57], v[66:69], v[160:163], v[54:57]
	v_mfma_f32_16x16x32_bf16 v[46:49], v[74:77], v[160:163], v[46:49]
	v_mfma_f32_16x16x32_bf16 v[38:41], v[66:69], v[178:181], v[38:41]
	v_mfma_f32_16x16x32_bf16 v[30:33], v[74:77], v[178:181], v[30:33]
	v_mfma_f32_16x16x32_bf16 v[22:25], v[66:69], v[186:189], v[22:25]
	v_mfma_f32_16x16x32_bf16 v[14:17], v[74:77], v[186:189], v[14:17]
	v_mfma_f32_16x16x32_bf16 v[62:65], v[70:73], v[156:159], v[62:65]
	v_mfma_f32_16x16x32_bf16 v[58:61], v[78:81], v[156:159], v[58:61]
	v_mfma_f32_16x16x32_bf16 v[54:57], v[70:73], v[168:171], v[54:57]
	v_mfma_f32_16x16x32_bf16 v[46:49], v[78:81], v[168:171], v[46:49]
	v_mfma_f32_16x16x32_bf16 v[38:41], v[70:73], v[182:185], v[38:41]
	v_mfma_f32_16x16x32_bf16 v[30:33], v[78:81], v[182:185], v[30:33]
	v_mfma_f32_16x16x32_bf16 v[22:25], v[70:73], v[202:205], v[22:25]
	v_mfma_f32_16x16x32_bf16 v[14:17], v[78:81], v[202:205], v[14:17]

	s_barrier
	s_add_u32 s18, s54, 0xb0080
	s_addc_u32 s19, s55, 0
	s_add_i32 s54, s56, s40
	v_lshl_add_u64 v[66:67], s[18:19], 0, v[0:1]
	s_mov_b32 m0, s54
	s_nop 0
	global_load_lds_dwordx4 v[66:67], off
	v_lshl_add_u64 v[66:67], s[18:19], 0, v[146:147]
	s_add_i32 m0, s54, 0x2000
	s_nop 0
	global_load_lds_dwordx4 v[66:67], off
	s_waitcnt vmcnt(6)
	s_barrier

	v_mfma_f32_16x16x32_bf16 v[50:53], v[210:213], v[152:155], v[50:53]
	v_mfma_f32_16x16x32_bf16 v[42:45], v[218:221], v[152:155], v[42:45]
	v_mfma_f32_16x16x32_bf16 v[34:37], v[210:213], v[160:163], v[34:37]
	v_mfma_f32_16x16x32_bf16 v[26:29], v[218:221], v[160:163], v[26:29]
	v_mfma_f32_16x16x32_bf16 v[18:21], v[210:213], v[178:181], v[18:21]
	v_mfma_f32_16x16x32_bf16 v[10:13], v[218:221], v[178:181], v[10:13]
	v_mfma_f32_16x16x32_bf16 v[6:9], v[210:213], v[186:189], v[6:9]
	v_mfma_f32_16x16x32_bf16 v[2:5], v[218:221], v[186:189], v[2:5]
	v_mfma_f32_16x16x32_bf16 v[50:53], v[214:217], v[156:159], v[50:53]
	v_mfma_f32_16x16x32_bf16 v[42:45], v[222:225], v[156:159], v[42:45]
	v_mfma_f32_16x16x32_bf16 v[34:37], v[214:217], v[168:171], v[34:37]
	v_mfma_f32_16x16x32_bf16 v[26:29], v[222:225], v[168:171], v[26:29]
	v_mfma_f32_16x16x32_bf16 v[18:21], v[214:217], v[182:185], v[18:21]
	v_mfma_f32_16x16x32_bf16 v[10:13], v[222:225], v[182:185], v[10:13]
	v_mfma_f32_16x16x32_bf16 v[6:9], v[214:217], v[202:205], v[6:9]
	v_mfma_f32_16x16x32_bf16 v[2:5], v[222:225], v[202:205], v[2:5]

	s_add_i32 s94, s94, 2
	s_add_u32 s22, s22, 0x100
	s_addc_u32 s23, s23, 0
	s_cmp_gt_u32 s94, 41
	s_mov_b64 s[18:19], s[52:53]
	s_barrier
	s_cbranch_scc0 .LBB0_1049
	s_sub_i32 s18, s90, 32
	s_lshr_b32 s18, s18, 2
	s_add_i32 s18, s18, 1
	s_cmp_gt_i32 s90, 31
	v_lshl_or_b32 v66, s91, 8, v166
	s_cselect_b32 s18, s18, 0
	s_mul_hi_u32 s19, s18, 0x6000
	s_mulk_i32 s18, 0x6000
	v_ashrrev_i32_e32 v67, 31, v66
	v_lshl_add_u32 v162, s90, 8, v164
	s_add_u32 s18, s59, s18
	v_lshlrev_b64 v[152:153], 2, v[66:67]
	v_ashrrev_i32_e32 v163, 31, v162
	s_addc_u32 s19, s62, s19
	v_lshl_add_u64 v[154:155], s[26:27], 0, v[152:153]
	v_lshlrev_b64 v[156:157], 12, v[162:163]
	v_lshl_add_u64 v[66:67], s[18:19], 0, v[152:153]
	v_lshl_add_u64 v[172:173], v[154:155], 0, v[156:157]
	global_load_dwordx4 v[78:81], v[66:67], off
	global_load_dwordx4 v[74:77], v[66:67], off offset:64
	global_load_dwordx4 v[70:73], v[66:67], off offset:512
	s_nop 0
	global_load_dwordx4 v[66:69], v[66:67], off offset:576
	s_nop 0
	global_load_dwordx4 v[158:161], v[172:173], off
	global_load_dwordx4 v[168:171], v[172:173], off offset:64
	global_load_dwordx4 v[178:181], v[172:173], off offset:512
	global_load_dwordx4 v[182:185], v[172:173], off offset:576
	v_or_b32_e32 v172, 16, v162
	v_ashrrev_i32_e32 v173, 31, v172
	v_lshlrev_b64 v[172:173], 12, v[172:173]
	v_lshl_add_u64 v[190:191], v[154:155], 0, v[172:173]
	global_load_dwordx4 v[186:189], v[190:191], off
	global_load_dwordx4 v[210:213], v[190:191], off offset:64
	global_load_dwordx4 v[214:217], v[190:191], off offset:512
	global_load_dwordx4 v[218:221], v[190:191], off offset:576
	v_or_b32_e32 v190, 32, v162
	v_ashrrev_i32_e32 v191, 31, v190
	v_lshlrev_b64 v[190:191], 12, v[190:191]
	v_or_b32_e32 v162, 48, v162
	v_lshl_add_u64 v[202:203], v[154:155], 0, v[190:191]
	v_ashrrev_i32_e32 v163, 31, v162
	global_load_dwordx4 v[222:225], v[202:203], off
	global_load_dwordx4 v[226:229], v[202:203], off offset:64
	global_load_dwordx4 v[230:233], v[202:203], off offset:512
	global_load_dwordx4 v[234:237], v[202:203], off offset:576
	v_lshlrev_b64 v[162:163], 12, v[162:163]
	v_lshl_add_u64 v[202:203], v[154:155], 0, v[162:163]
	global_load_dwordx4 v[238:241], v[202:203], off
	global_load_dwordx4 v[242:245], v[202:203], off offset:64
	global_load_dwordx4 v[246:249], v[202:203], off offset:512
	s_nop 0
	global_load_dwordx4 v[202:205], v[202:203], off offset:576
	s_mov_b64 s[18:19], 0x80000
	s_and_b64 vcc, exec, s[2:3]
	s_mov_b32 s91, s66
	s_mov_b32 s90, s67
	s_mov_b64 s[52:53], s[0:1]
	s_waitcnt vmcnt(0)
	v_pk_fma_f32 v[142:143], v[142:143], v[78:79], v[158:159]
	v_lshl_add_u64 v[158:159], s[26:27], 0, v[156:157]
	v_lshl_add_u64 v[158:159], v[158:159], 0, v[152:153]
	v_pk_fma_f32 v[128:129], v[128:129], v[72:73], v[180:181]
	v_pk_fma_f32 v[126:127], v[126:127], v[70:71], v[178:179]
	global_store_dwordx4 v[158:159], v[126:129], off offset:512
	v_pk_fma_f32 v[120:121], v[120:121], v[68:69], v[184:185]
	v_pk_fma_f32 v[112:113], v[112:113], v[72:73], v[216:217]
	v_lshl_add_u64 v[126:127], s[26:27], 0, v[172:173]
	v_lshl_add_u64 v[126:127], v[126:127], 0, v[152:153]
	v_pk_fma_f32 v[110:111], v[110:111], v[70:71], v[214:215]
	global_store_dwordx4 v[126:127], v[110:113], off offset:512
	v_pk_fma_f32 v[118:119], v[118:119], v[66:67], v[182:183]
	v_pk_fma_f32 v[104:105], v[104:105], v[68:69], v[220:221]
	v_lshl_add_u64 v[110:111], s[26:27], 0, v[190:191]
	v_lshl_add_u64 v[110:111], v[110:111], 0, v[152:153]
	v_pk_fma_f32 v[96:97], v[96:97], v[72:73], v[232:233]
	v_pk_fma_f32 v[94:95], v[94:95], v[70:71], v[230:231]
	v_pk_fma_f32 v[102:103], v[102:103], v[66:67], v[218:219]
	global_store_dwordx4 v[110:111], v[94:97], off offset:512
	v_pk_fma_f32 v[92:93], v[92:93], v[68:69], v[236:237]
	v_pk_fma_f32 v[90:91], v[90:91], v[66:67], v[234:235]
	v_lshl_add_u64 v[94:95], s[26:27], 0, v[162:163]
	global_store_dwordx4 v[158:159], v[118:121], off offset:576
	global_store_dwordx4 v[126:127], v[102:105], off offset:576
	global_store_dwordx4 v[110:111], v[90:93], off offset:576
	v_pk_fma_f32 v[120:121], v[136:137], v[80:81], v[188:189]
	v_pk_fma_f32 v[118:119], v[134:135], v[78:79], v[186:187]
	v_pk_fma_f32 v[104:105], v[124:125], v[80:81], v[224:225]
	v_pk_fma_f32 v[102:103], v[122:123], v[78:79], v[222:223]
	v_pk_fma_f32 v[92:93], v[108:109], v[80:81], v[240:241]
	v_pk_fma_f32 v[90:91], v[106:107], v[78:79], v[238:239]
	v_lshl_add_u64 v[94:95], v[94:95], 0, v[152:153]
	v_pk_fma_f32 v[144:145], v[144:145], v[80:81], v[160:161]
	v_pk_fma_f32 v[140:141], v[140:141], v[76:77], v[170:171]
	v_pk_fma_f32 v[138:139], v[138:139], v[74:75], v[168:169]
	global_store_dwordx4 v[126:127], v[118:121], off
	global_store_dwordx4 v[110:111], v[102:105], off
	global_store_dwordx4 v[94:95], v[90:93], off
	v_pk_fma_f32 v[120:121], v[132:133], v[76:77], v[212:213]
	v_pk_fma_f32 v[118:119], v[130:131], v[74:75], v[210:211]
	v_pk_fma_f32 v[104:105], v[116:117], v[76:77], v[228:229]
	v_pk_fma_f32 v[102:103], v[114:115], v[74:75], v[226:227]
	v_pk_fma_f32 v[92:93], v[100:101], v[76:77], v[244:245]
	v_pk_fma_f32 v[90:91], v[98:99], v[74:75], v[242:243]
	v_pk_fma_f32 v[88:89], v[88:89], v[72:73], v[248:249]
	v_pk_fma_f32 v[86:87], v[86:87], v[70:71], v[246:247]
	v_pk_fma_f32 v[84:85], v[84:85], v[68:69], v[204:205]
	v_pk_fma_f32 v[82:83], v[82:83], v[66:67], v[202:203]
	v_lshl_add_u64 v[162:163], v[156:157], 0, s[18:19]
	global_store_dwordx4 v[158:159], v[142:145], off
	global_store_dwordx4 v[158:159], v[138:141], off offset:64
	global_store_dwordx4 v[126:127], v[118:121], off offset:64
	global_store_dwordx4 v[110:111], v[102:105], off offset:64
	global_store_dwordx4 v[94:95], v[90:93], off offset:64
	global_store_dwordx4 v[94:95], v[86:89], off offset:512
	global_store_dwordx4 v[94:95], v[82:85], off offset:576
	s_mov_b64 s[18:19], 0x90000
	v_lshl_add_u64 v[160:161], v[156:157], 0, s[18:19]
	v_lshl_add_u64 v[82:83], v[154:155], 0, v[162:163]
	global_load_dwordx4 v[126:129], v[82:83], off
	global_load_dwordx4 v[122:125], v[82:83], off offset:64
	global_load_dwordx4 v[118:121], v[82:83], off offset:512
	global_load_dwordx4 v[106:109], v[82:83], off offset:576
	v_lshl_add_u64 v[82:83], v[154:155], 0, v[160:161]
	s_mov_b64 s[18:19], 0xa0000
	global_load_dwordx4 v[114:117], v[82:83], off
	global_load_dwordx4 v[102:105], v[82:83], off offset:64
	global_load_dwordx4 v[94:97], v[82:83], off offset:512
	global_load_dwordx4 v[86:89], v[82:83], off offset:576
	v_lshl_add_u64 v[158:159], v[156:157], 0, s[18:19]
	v_lshl_add_u64 v[82:83], v[154:155], 0, v[158:159]
	s_mov_b64 s[18:19], 0xb0000
	global_load_dwordx4 v[110:113], v[82:83], off
	global_load_dwordx4 v[98:101], v[82:83], off offset:64
	global_load_dwordx4 v[90:93], v[82:83], off offset:512
	s_nop 0
	global_load_dwordx4 v[82:85], v[82:83], off offset:576
	v_lshl_add_u64 v[156:157], v[156:157], 0, s[18:19]
	v_lshl_add_u64 v[134:135], v[154:155], 0, v[156:157]
	global_load_dwordx4 v[130:133], v[134:135], off
	global_load_dwordx4 v[142:145], v[134:135], off offset:64
	global_load_dwordx4 v[138:141], v[134:135], off offset:512
	s_nop 0
	global_load_dwordx4 v[134:137], v[134:135], off offset:576
	s_mov_b64 s[18:19], s[4:5]
	s_waitcnt vmcnt(0)
	v_pk_fma_f32 v[62:63], v[62:63], v[78:79], v[126:127]
	v_lshl_add_u64 v[126:127], s[26:27], 0, v[162:163]
	v_lshl_add_u64 v[126:127], v[126:127], 0, v[152:153]
	v_pk_fma_f32 v[52:53], v[52:53], v[72:73], v[120:121]
	v_pk_fma_f32 v[50:51], v[50:51], v[70:71], v[118:119]
	global_store_dwordx4 v[126:127], v[50:53], off offset:512
	v_pk_fma_f32 v[36:37], v[36:37], v[72:73], v[96:97]
	v_pk_fma_f32 v[34:35], v[34:35], v[70:71], v[94:95]
	v_lshl_add_u64 v[50:51], s[26:27], 0, v[160:161]
	v_lshl_add_u64 v[50:51], v[50:51], 0, v[152:153]
	global_store_dwordx4 v[50:51], v[34:37], off offset:512
	v_pk_fma_f32 v[20:21], v[20:21], v[72:73], v[92:93]
	v_pk_fma_f32 v[18:19], v[18:19], v[70:71], v[90:91]
	v_lshl_add_u64 v[34:35], s[26:27], 0, v[158:159]
	v_lshl_add_u64 v[34:35], v[34:35], 0, v[152:153]
	v_pk_fma_f32 v[44:45], v[44:45], v[68:69], v[108:109]
	v_pk_fma_f32 v[42:43], v[42:43], v[66:67], v[106:107]
	v_pk_fma_f32 v[28:29], v[28:29], v[68:69], v[88:89]
	v_pk_fma_f32 v[26:27], v[26:27], v[66:67], v[86:87]
	global_store_dwordx4 v[34:35], v[18:21], off offset:512
	v_pk_fma_f32 v[12:13], v[12:13], v[68:69], v[84:85]
	v_pk_fma_f32 v[10:11], v[10:11], v[66:67], v[82:83]
	v_lshl_add_u64 v[18:19], s[26:27], 0, v[156:157]
	global_store_dwordx4 v[126:127], v[42:45], off offset:576
	global_store_dwordx4 v[50:51], v[26:29], off offset:576
	global_store_dwordx4 v[34:35], v[10:13], off offset:576
	v_pk_fma_f32 v[44:45], v[56:57], v[80:81], v[116:117]
	v_pk_fma_f32 v[42:43], v[54:55], v[78:79], v[114:115]
	v_pk_fma_f32 v[28:29], v[40:41], v[80:81], v[112:113]
	v_pk_fma_f32 v[26:27], v[38:39], v[78:79], v[110:111]
	v_pk_fma_f32 v[12:13], v[24:25], v[80:81], v[132:133]
	v_pk_fma_f32 v[10:11], v[22:23], v[78:79], v[130:131]
	v_lshl_add_u64 v[18:19], v[18:19], 0, v[152:153]
	v_pk_fma_f32 v[64:65], v[64:65], v[80:81], v[128:129]
	v_pk_fma_f32 v[60:61], v[60:61], v[76:77], v[124:125]
	v_pk_fma_f32 v[58:59], v[58:59], v[74:75], v[122:123]
	global_store_dwordx4 v[50:51], v[42:45], off
	global_store_dwordx4 v[34:35], v[26:29], off
	global_store_dwordx4 v[18:19], v[10:13], off
	v_pk_fma_f32 v[44:45], v[48:49], v[76:77], v[104:105]
	v_pk_fma_f32 v[42:43], v[46:47], v[74:75], v[102:103]
	v_pk_fma_f32 v[28:29], v[32:33], v[76:77], v[100:101]
	v_pk_fma_f32 v[26:27], v[30:31], v[74:75], v[98:99]
	v_pk_fma_f32 v[12:13], v[16:17], v[76:77], v[144:145]
	v_pk_fma_f32 v[10:11], v[14:15], v[74:75], v[142:143]
	v_pk_fma_f32 v[8:9], v[8:9], v[72:73], v[140:141]
	v_pk_fma_f32 v[6:7], v[6:7], v[70:71], v[138:139]
	v_pk_fma_f32 v[4:5], v[4:5], v[68:69], v[136:137]
	v_pk_fma_f32 v[2:3], v[2:3], v[66:67], v[134:135]
	global_store_dwordx4 v[126:127], v[62:65], off
	global_store_dwordx4 v[126:127], v[58:61], off offset:64
	global_store_dwordx4 v[50:51], v[42:45], off offset:64
	global_store_dwordx4 v[34:35], v[26:29], off offset:64
	global_store_dwordx4 v[18:19], v[10:13], off offset:64
	global_store_dwordx4 v[18:19], v[6:9], off offset:512
	global_store_dwordx4 v[18:19], v[2:5], off offset:576
	s_cbranch_vccz .LBB0_1042
	s_waitcnt vmcnt(0)
	v_readlane_b32 s66, v252, 44
	v_readlane_b32 s64, v254, 62
	v_readlane_b32 s90, v255, 0
	s_cmpk_gt_u32 s14, 0xff
	v_readlane_b32 s67, v252, 45
	v_readlane_b32 s65, v254, 63
	v_readlane_b32 s91, v255, 1
	s_cbranch_scc1 .LBB0_1053
	s_barrier
